# instruction placement: every 8-byte instruction of the scan loop on an 8-byte boundary (e32->e64 widening or s_nop padding)
# baseline (speedup 1.0000x reference)
.LBB0_672:
	s_nop 0
	s_add_i32 s22, s65, 1
	s_and_b32 s23, s65, 1
	s_mov_b32 s24, 0
	v_and_b32_e32 v224, 63, v64
	v_and_b32_e32 v233, 15, v224
	v_lshrrev_b32_e32 v234, 4, v224
	s_mov_b32 s98, 0
	s_mov_b32 s99, -1
	v_mov_b32_e32 v235, 0
	s_cmp_lg_u32 s65, 0
	s_cbranch_scc1 .Lmy_f_main
	s_nop 0
	s_bfe_u32 s96, s62, 0x20006
	s_lshl_b32 s100, s96, 11
	s_nop 0
	v_lshl_add_u32 v72, v224, 2, s100
	s_mul_i32 s97, s96, 0x2700
	s_cmp_gt_u32 s96, 1
	s_nop 0
	s_cselect_b32 s101, 0x1300, 0
	s_add_i32 s97, s97, s101
	s_nop 0
	s_add_i32 s97, s97, 0x1c000
	ds_read_b32 v80, v72
	ds_read_b32 v81, v72 offset:256
	ds_read_b32 v82, v72 offset:512
	ds_read_b32 v83, v72 offset:768
	ds_read_b32 v84, v72 offset:1024
	ds_read_b32 v85, v72 offset:1280
	ds_read_b32 v86, v72 offset:1536
	ds_read_b32 v87, v72 offset:1792
	s_cmpk_ge_u32 s62, 0x100
	s_cbranch_scc1 .Lmy_ck_drB_a
	ds_read_b32 v88, v72 offset:8192
	ds_read_b32 v89, v72 offset:8448
	ds_read_b32 v90, v72 offset:8704
	ds_read_b32 v91, v72 offset:8960
	ds_read_b32 v92, v72 offset:9216
	ds_read_b32 v93, v72 offset:9472
	ds_read_b32 v94, v72 offset:9728
	ds_read_b32 v95, v72 offset:9984
	ds_read_b32 v96, v72 offset:32768
	ds_read_b32 v97, v72 offset:33024
	ds_read_b32 v98, v72 offset:33280
	ds_read_b32 v99, v72 offset:33536
	ds_read_b32 v100, v72 offset:33792
	ds_read_b32 v101, v72 offset:34048
	ds_read_b32 v102, v72 offset:34304
	ds_read_b32 v103, v72 offset:34560
	v_and_b32_e64 v74, 3, v224
	v_bfe_u32 v75, v224, 2, 2
	v_lshrrev_b32_e32 v76, 4, v224
	v_lshlrev_b32_e32 v74, 2, v74
	v_lshl_add_u32 v74, v75, 8, v74
	v_lshl_add_u32 v74, v76, 10, v74
	s_add_i32 s100, s97, 0x0
	v_add_u32_e32 v74, s100, v74
	v_xor_b32_e32 v76, 0, v75
	v_xor_b32_e32 v77, 1, v75
	v_xor_b32_e32 v78, 2, v75
	v_xor_b32_e32 v79, 3, v75
	v_lshl_add_u32 v76, v76, 4, v74
	v_lshl_add_u32 v77, v77, 4, v74
	v_lshl_add_u32 v78, v78, 4, v74
	v_lshl_add_u32 v79, v79, 4, v74
	s_waitcnt lgkmcnt(15)
	v_mov_b32_e32 v104, v80
	v_mul_f32_e32 v105, v104, v81
	v_mul_f32_e32 v106, v105, v82
	v_mul_f32_e32 v107, v106, v83
	v_mul_f32_e32 v108, v107, v84
	v_mul_f32_e32 v109, v108, v85
	v_mul_f32_e32 v110, v109, v86
	v_mul_f32_e32 v111, v110, v87
	v_mov_b32_e32 v112, v88
	s_waitcnt lgkmcnt(14)
	v_mul_f32_e32 v113, v104, v89
	s_waitcnt lgkmcnt(13)
	v_mul_f32_e32 v114, v105, v90
	s_waitcnt lgkmcnt(12)
	v_mul_f32_e32 v115, v106, v91
	s_waitcnt lgkmcnt(11)
	v_mul_f32_e32 v116, v107, v92
	s_waitcnt lgkmcnt(10)
	v_mul_f32_e32 v117, v108, v93
	s_waitcnt lgkmcnt(9)
	v_mul_f32_e32 v118, v109, v94
	s_waitcnt lgkmcnt(8)
	v_mul_f32_e32 v119, v110, v95
	s_waitcnt lgkmcnt(7)
	v_mul_f32_e32 v120, v104, v96
	s_waitcnt lgkmcnt(6)
	v_mul_f32_e32 v121, v105, v97
	s_waitcnt lgkmcnt(5)
	v_mul_f32_e32 v122, v106, v98
	s_waitcnt lgkmcnt(4)
	v_mul_f32_e32 v123, v107, v99
	s_waitcnt lgkmcnt(3)
	v_mul_f32_e32 v124, v108, v100
	s_waitcnt lgkmcnt(2)
	v_mul_f32_e32 v125, v109, v101
	s_waitcnt lgkmcnt(1)
	v_mul_f32_e32 v126, v110, v102
	s_waitcnt lgkmcnt(0)
	v_mul_f32_e32 v127, v111, v103
	ds_write_b32 v76, v112
	ds_write_b32 v77, v113
	ds_write_b32 v78, v114
	ds_write_b32 v79, v115
	ds_write_b32 v76, v116 offset:64
	ds_write_b32 v77, v117 offset:64
	ds_write_b32 v78, v118 offset:64
	ds_write_b32 v79, v119 offset:64
	ds_write_b32 v76, v120 offset:128
	ds_write_b32 v77, v121 offset:128
	ds_write_b32 v78, v122 offset:128
	ds_write_b32 v79, v123 offset:128
	ds_write_b32 v76, v124 offset:192
	ds_write_b32 v77, v125 offset:192
	ds_write_b32 v78, v126 offset:192
	ds_write_b32 v79, v127 offset:192
	s_branch .Lmy_ck_drE_a
.Lmy_ck_drB_a:
	s_waitcnt lgkmcnt(0)
	ds_read_b32 v88, v72 offset:16384
	ds_read_b32 v89, v72 offset:16640
	ds_read_b32 v90, v72 offset:16896
	ds_read_b32 v91, v72 offset:17152
	ds_read_b32 v92, v72 offset:17408
	ds_read_b32 v93, v72 offset:17664
	ds_read_b32 v94, v72 offset:17920
	ds_read_b32 v95, v72 offset:18176
	ds_read_b32 v96, v72 offset:24576
	ds_read_b32 v97, v72 offset:24832
	ds_read_b32 v98, v72 offset:25088
	ds_read_b32 v99, v72 offset:25344
	ds_read_b32 v100, v72 offset:25600
	ds_read_b32 v101, v72 offset:25856
	ds_read_b32 v102, v72 offset:26112
	ds_read_b32 v103, v72 offset:26368
	v_and_b32_e32 v74, 15, v224
	v_lshrrev_b32_e32 v76, 4, v224
	v_lshlrev_b32_e64 v74, 4, v74
	v_lshl_add_u32 v74, v76, 10, v74
	s_add_i32 s101, s97, 0x1000
	v_add_u32_e64 v74, s101, v74
	s_add_i32 s101, s97, 0x2000
	v_lshl_add_u32 v75, v224, 2, s101
	v_mov_b32_e32 v104, v80
	v_mul_f32_e32 v105, v104, v81
	v_mul_f32_e32 v106, v105, v82
	v_mul_f32_e32 v107, v106, v83
	v_mul_f32_e32 v108, v107, v84
	v_mul_f32_e32 v109, v108, v85
	v_mul_f32_e32 v110, v109, v86
	v_mul_f32_e32 v111, v110, v87
	v_rcp_f32_e32 v112, v104
	v_rcp_f32_e32 v113, v105
	v_rcp_f32_e32 v114, v106
	v_rcp_f32_e32 v115, v107
	v_rcp_f32_e32 v116, v108
	v_rcp_f32_e32 v117, v109
	v_rcp_f32_e32 v118, v110
	v_rcp_f32_e32 v119, v111
	s_waitcnt lgkmcnt(7)
	v_mul_f32_e32 v120, v112, v96
	s_waitcnt lgkmcnt(6)
	v_mul_f32_e32 v121, v113, v97
	s_waitcnt lgkmcnt(5)
	v_mul_f32_e32 v122, v114, v98
	s_waitcnt lgkmcnt(4)
	v_mul_f32_e32 v123, v115, v99
	s_waitcnt lgkmcnt(3)
	v_mul_f32_e32 v124, v116, v100
	s_waitcnt lgkmcnt(2)
	v_mul_f32_e32 v125, v117, v101
	s_waitcnt lgkmcnt(1)
	v_mul_f32_e32 v126, v118, v102
	s_waitcnt lgkmcnt(0)
	v_mul_f32_e32 v127, v119, v103
	v_mul_f32_e32 v112, v112, v88
	v_mul_f32_e32 v113, v113, v89
	v_mul_f32_e32 v114, v114, v90
	v_mul_f32_e32 v115, v115, v91
	v_mul_f32_e32 v116, v116, v92
	v_mul_f32_e32 v117, v117, v93
	v_mul_f32_e32 v118, v118, v94
	v_mul_f32_e32 v119, v119, v95
	ds_write_b128 v74, v[112:115]
	ds_write_b128 v74, v[116:119] offset:256
	ds_write_b128 v74, v[120:123] offset:512
	ds_write_b128 v74, v[124:127] offset:768
	ds_write_b32 v75, v111
.Lmy_ck_drE_a:
	s_waitcnt lgkmcnt(0)
	s_barrier
	s_cmpk_ge_u32 s62, 0x100
	s_cbranch_scc1 .Lmy_ck_mE_a
	s_bfe_u32 s96, s62, 0x20006
	s_mul_i32 s97, s96, 0x2700
	s_cmp_gt_u32 s96, 1
	s_nop 0
	s_cselect_b32 s101, 0x1300, 0
	s_add_i32 s97, s97, s101
	s_nop 0
	s_add_i32 s97, s97, 0x1c000
	s_mov_b32 s96, s97
	v_and_b32_e32 v72, 3, v233
	v_lshrrev_b32_e32 v73, 2, v233
	v_lshlrev_b32_e32 v72, 2, v72
	v_lshl_add_u32 v72, v73, 8, v72
	v_lshl_add_u32 v72, v234, 6, v72
	s_add_i32 s97, s96, 0x1000
	v_add_u32_e32 v78, s97, v72
	v_xor_b32_e32 v79, v224, v234
	v_lshl_add_u32 v79, v79, 4, s96
	ds_read_b128 v[96:99], v79
	ds_read_b128 v[100:103], v79 offset:1024
	ds_read_b128 v[104:107], v79 offset:2048
	ds_read_b128 v[108:111], v79 offset:3072
	ds_read_b32 v80, v78
	ds_read_b32 v81, v78 offset:16
	ds_read_b32 v82, v78 offset:32
	ds_read_b32 v83, v78 offset:48
	ds_read_b32 v84, v78 offset:1024
	ds_read_b32 v85, v78 offset:1040
	ds_read_b32 v86, v78 offset:1056
	ds_read_b32 v87, v78 offset:1072
	ds_read_b32 v88, v78 offset:2048
	ds_read_b32 v89, v78 offset:2064
	ds_read_b32 v90, v78 offset:2080
	ds_read_b32 v91, v78 offset:2096
	ds_read_b32 v92, v78 offset:3072
	ds_read_b32 v93, v78 offset:3088
	ds_read_b32 v94, v78 offset:3104
	ds_read_b32 v95, v78 offset:3120
	v_lshl_add_u32 v74, v224, 2, s96
	ds_write_b32 v74, v235 offset:9728
	v_add_u32_e32 v75, -1, v233
	v_mov_b32_e32 v76, -1
	v_cndmask_b32_e64 v75, v76, v75, s[98:99]
	v_cmp_lt_u32_e64 s[100:101], 7, v233
	v_add_u32_e32 v76, -8, v233
	v_and_b32_e32 v77, 1, v234
	v_cndmask_b32_e64 v75, v75, v76, s[100:101]
	v_lshlrev_b32_e32 v77, 2, v77
	v_sub_u32_e32 v76, v75, v77
	v_lshlrev_b32_e32 v77, 2, v234
	v_sub_u32_e32 v77, v233, v77
	v_add_u32_e32 v77, -1, v77
	s_waitcnt lgkmcnt(15)
	v_mfma_f32_16x16x4_f32 v[244:247], v80, v96, 0
	v_mfma_f32_16x16x4_f32 v[240:243], v81, v97, 0
	s_waitcnt lgkmcnt(14)
	s_nop 0
	v_mfma_f32_16x16x4_f32 v[244:247], v82, v98, v[244:247]
	s_waitcnt lgkmcnt(13)
	s_nop 0
	v_mfma_f32_16x16x4_f32 v[240:243], v83, v99, v[240:243]
	s_waitcnt lgkmcnt(12)
	s_nop 0
	v_mfma_f32_16x16x4_f32 v[244:247], v84, v100, v[244:247]
	s_waitcnt lgkmcnt(11)
	s_nop 0
	v_mfma_f32_16x16x4_f32 v[240:243], v85, v101, v[240:243]
	s_waitcnt lgkmcnt(10)
	s_nop 0
	v_mfma_f32_16x16x4_f32 v[244:247], v86, v102, v[244:247]
	s_waitcnt lgkmcnt(9)
	s_nop 0
	v_mfma_f32_16x16x4_f32 v[240:243], v87, v103, v[240:243]
	s_waitcnt lgkmcnt(8)
	s_nop 0
	v_mfma_f32_16x16x4_f32 v[244:247], v88, v104, v[244:247]
	s_waitcnt lgkmcnt(7)
	s_nop 0
	v_mfma_f32_16x16x4_f32 v[240:243], v89, v105, v[240:243]
	s_waitcnt lgkmcnt(6)
	s_nop 0
	v_mfma_f32_16x16x4_f32 v[244:247], v90, v106, v[244:247]
	s_waitcnt lgkmcnt(5)
	s_nop 0
	v_mfma_f32_16x16x4_f32 v[240:243], v91, v107, v[240:243]
	s_waitcnt lgkmcnt(4)
	s_nop 0
	v_mfma_f32_16x16x4_f32 v[244:247], v92, v108, v[244:247]
	s_waitcnt lgkmcnt(3)
	s_nop 0
	v_mfma_f32_16x16x4_f32 v[240:243], v93, v109, v[240:243]
	s_waitcnt lgkmcnt(2)
	s_nop 0
	v_mfma_f32_16x16x4_f32 v[244:247], v94, v110, v[244:247]
	s_waitcnt lgkmcnt(1)
	s_nop 0
	v_mfma_f32_16x16x4_f32 v[240:243], v95, v111, v[240:243]
	s_nop 9
	v_add_f32_e32 v244, v244, v240
	v_add_f32_e32 v245, v245, v241
	v_add_f32_e32 v246, v246, v242
	v_add_f32_e64 v247, v247, v243
	v_cmp_le_i32_e64 s[96:97], 0, v76
	v_cmp_le_i32_e64 s[100:101], 1, v76
	s_nop 0
	s_nop 0
	v_cndmask_b32_e64 v128, 0, v244, s[96:97]
	v_cndmask_b32_e64 v129, 0, v245, s[100:101]
	v_cmp_le_i32_e64 s[96:97], 2, v76
	v_cmp_le_i32_e64 s[100:101], 3, v76
	s_nop 0
	s_nop 0
	v_cndmask_b32_e64 v130, 0, v246, s[96:97]
	v_cndmask_b32_e64 v131, 0, v247, s[100:101]
	s_bfe_u32 s96, s62, 0x20006
	s_mul_i32 s97, s96, 0x2700
	s_cmp_gt_u32 s96, 1
	s_nop 0
	s_cselect_b32 s101, 0x1300, 0
	s_add_i32 s97, s97, s101
	s_nop 0
	s_add_i32 s97, s97, 0x1c000
	v_xor_b32_e64 v74, v224, v234
	v_lshl_add_u32 v74, v74, 4, s97
	ds_write_b128 v74, v[128:131] offset:8448
	v_lshlrev_b32_e64 v75, 7, v234
	v_lshl_add_u32 v75, v233, 2, v75
	v_add_u32_e64 v75, s97, v75
	v_cmp_le_i32_e64 s[96:97], 0, v77
	v_cmp_le_i32_e64 s[100:101], 1, v77
	s_nop 0
	s_nop 0
	v_cndmask_b32_e64 v132, 0, v244, s[96:97]
	v_cndmask_b32_e64 v133, 0, v245, s[100:101]
	v_cmp_le_i32_e64 s[96:97], 2, v77
	v_cmp_le_i32_e64 s[100:101], 3, v77
	s_nop 0
	s_nop 0
	v_cndmask_b32_e64 v134, 0, v246, s[96:97]
	v_cndmask_b32_e64 v135, 0, v247, s[100:101]
	s_mov_b64 exec, 0x00ff00ff
	ds_write_b32 v75, v132 offset:9472
	ds_write_b32 v75, v133 offset:9504
	ds_write_b32 v75, v134 offset:9536
	ds_write_b32 v75, v135 offset:9568
	s_mov_b64 exec, -1

.Lmy_f_main:
	s_cmpk_ge_u32 s62, 0x100
	s_cbranch_scc1 .Lmy_f_hlp
	s_cmp_lg_u32 s65, 0
	s_cbranch_scc1 .Lmy_ck_nz
	v_mov_b32_e32 v208, 0
	v_mov_b32_e32 v209, 0
	v_mov_b32_e32 v210, 0
	v_mov_b32_e32 v211, 0
	v_mov_b32_e32 v212, 0
	v_mov_b32_e32 v213, 0
	v_mov_b32_e32 v214, 0
	v_mov_b32_e32 v215, 0
	v_mov_b32_e32 v216, 0
	v_mov_b32_e32 v217, 0
	v_mov_b32_e32 v218, 0
	v_mov_b32_e32 v219, 0
	v_mov_b32_e32 v220, 0
	v_mov_b32_e32 v221, 0
	v_mov_b32_e32 v222, 0
	v_mov_b32_e32 v223, 0
	v_xor_b32_e32 v1, v224, v234
	v_lshlrev_b32_e32 v1, 4, v1
	v_lshlrev_b32_e32 v2, 4, v234
	v_add_u32_e32 v2, 0x2000, v2
	v_mov_b32_e32 v72, 0x2600
	v_mov_b32_e32 v73, 0x2500
	v_mov_b32_e32 v74, 0x2510
	v_mov_b32_e32 v75, 0x2590
	v_cmp_eq_u32_e64 s[96:97], 0, v234
	v_and_b32_e32 v76, 1, v234
	v_lshrrev_b32_e32 v77, 1, v234
	v_cndmask_b32_e64 v3, v72, v73, s[96:97]
	v_cmp_eq_u32_e64 s[96:97], 1, v234
	v_and_b32_e32 v78, 1, v234
	v_add_u32_e32 v79, 2, v77
	v_cndmask_b32_e64 v4, v72, v74, s[96:97]
	v_cndmask_b32_e64 v5, v72, v75, s[96:97]
	v_lshlrev_b32_e64 v76, 10, v76
	v_lshl_add_u32 v76, v233, 2, v76
	v_add_u32_e32 v8, s62, v76
	v_lshlrev_b32_e32 v76, 9, v234
	v_lshl_add_u32 v76, v233, 2, v76
	v_add_u32_e64 v9, s62, v76
	v_lshl_add_u32 v6, v79, 4, v233
	v_xor_b32_e32 v6, v6, v79
	v_lshlrev_b32_e32 v6, 4, v6
	v_lshl_add_u32 v6, v78, 3, v6
	v_add_u32_e32 v6, 0x2100, v6
	v_lshl_add_u32 v7, v78, 4, v233
	v_xor_b32_e32 v7, v7, v78
	v_lshlrev_b32_e32 v7, 4, v7
	v_lshl_add_u32 v7, v77, 3, v7
	v_add_u32_e32 v7, 0x2100, v7
	v_lshlrev_b32_e64 v0, 4, v233
	v_lshl_add_u32 v0, v78, 8, v0
	v_lshl_add_u32 v0, v77, 3, v0
	v_add_u32_e32 v0, 0x1000, v0
	v_lshlrev_b32_e64 v10, 4, v233
	v_lshl_add_u32 v10, v79, 8, v10
	v_lshl_add_u32 v10, v78, 3, v10
	v_add_u32_e32 v10, 0x1000, v10
	v_add_u32_e32 v232, 48, v224
	v_and_b32_e32 v232, 63, v232
	v_lshlrev_b32_e32 v232, 2, v232
.Lmy_ck_nz:
	s_nop 0
	s_mov_b32 s100, 0xe000
	s_cmp_eq_u32 s23, 0
	s_nop 0
	s_cselect_b32 s100, 0x1c000, s100
	s_mov_b32 s101, 0x12e00
	s_cselect_b32 s101, 0x22100, s101
	s_lshl_b32 s96, s23, 13
	s_nop 0
	s_add_i32 s97, s96, 0x18000
	s_add_i32 s96, s96, 0xa000
	v_add_u32_e32 v225, s100, v1
	v_add_u32_e32 v236, s100, v0
	v_add_u32_e32 v34, s100, v10
	v_add_u32_e32 v226, s100, v2
	v_add_u32_e32 v227, s100, v3
	v_add_u32_e32 v228, s100, v4
	v_add_u32_e32 v229, s100, v5
	v_add_u32_e32 v237, s100, v6
	v_add_u32_e32 v238, s100, v7
	v_add_u32_e32 v230, s96, v8
	v_add_u32_e32 v239, s96, v9
	v_add_u32_e32 v231, s97, v8
	v_add_u32_e32 v26, s101, v1
	v_add_u32_e32 v27, s101, v0
	v_add_u32_e32 v35, s101, v10
	v_add_u32_e32 v28, s101, v2
	v_add_u32_e32 v29, s101, v3
	v_add_u32_e32 v30, s101, v4
	v_add_u32_e32 v31, s101, v5
	v_add_u32_e32 v32, s101, v6
	v_add_u32_e64 v33, s101, v7
	ds_read_b64 v[80:81], v237
	ds_read_b64 v[82:83], v238
	ds_read_b32 v36, v239
	ds_read_b32 v37, v239 offset:256
	ds_read_b128 v[88:91], v225
	ds_read_b128 v[92:95], v225 offset:1024
	ds_read_b128 v[96:99], v225 offset:2048
	ds_read_b128 v[100:103], v225 offset:3072
	ds_read_b32 v104, v227 offset:4
	ds_read_b32 v105, v227 offset:76
	ds_read_b64 v[106:107], v227 offset:8
	ds_read_b64 v[108:109], v227 offset:40
	ds_read_b32 v126, v229 offset:4
	ds_read_b32 v127, v229 offset:76
	ds_read_b64 v[128:129], v229 offset:8
	ds_read_b64 v[130:131], v229 offset:40
	ds_read_b64 v[110:111], v228
	ds_read_b64 v[112:113], v228 offset:32
	ds_read_b64 v[114:115], v228 offset:64
	ds_read_b64 v[116:117], v228 offset:96
	ds_read_b64 v[118:119], v228 offset:8
	ds_read_b64 v[120:121], v228 offset:40
	ds_read_b64 v[122:123], v228 offset:72
	ds_read_b64 v[124:125], v228 offset:104
	s_waitcnt lgkmcnt(15)
	s_nop 0
	v_mfma_f32_16x16x4_f32 v[240:243], v80, v36, 0
	v_mfma_f32_16x16x4_f32 v[240:243], v81, v37, v[240:243]
	v_mfma_f32_16x16x4_f32 v[240:243], v88, v208, v[240:243]
	ds_read_b64 v[186:187], v34
	ds_read_b64 v[190:191], v34 offset:1024
	v_mfma_f32_16x16x4_f32 v[244:247], v89, v209, 0
	ds_read_b64 v[194:195], v34 offset:2048
	ds_read_b64 v[198:199], v34 offset:3072
	v_mfma_f32_16x16x4_f32 v[240:243], v90, v210, v[240:243]
	ds_read_b64 v[184:185], v236
	ds_read_b64 v[188:189], v236 offset:1024
	ds_read_b64 v[132:133], v237 offset:9984
	v_mfma_f32_16x16x4_f32 v[244:247], v91, v211, v[244:247]
	ds_read_b64 v[134:135], v238 offset:9984
	ds_read_b64 v[192:193], v236 offset:2048
	ds_read_b64 v[196:197], v236 offset:3072
	v_mfma_f32_16x16x4_f32 v[240:243], v92, v212, v[240:243]
	ds_read_b32 v38, v239 offset:2048
	ds_read_b32 v39, v239 offset:2304
	ds_read_b128 v[140:143], v225 offset:9984
	v_mfma_f32_16x16x4_f32 v[244:247], v93, v213, v[244:247]
	ds_read_b128 v[144:147], v225 offset:11008
	ds_read_b128 v[148:151], v225 offset:12032
	ds_read_b128 v[152:155], v225 offset:13056
	v_mfma_f32_16x16x4_f32 v[240:243], v94, v214, v[240:243]
	ds_read_b32 v156, v227 offset:9988
	ds_read_b32 v157, v227 offset:10060
	v_mfma_f32_16x16x4_f32 v[244:247], v95, v215, v[244:247]
	ds_read_b64 v[158:159], v227 offset:9992
	ds_read_b64 v[160:161], v227 offset:10024
	v_mfma_f32_16x16x4_f32 v[240:243], v96, v216, v[240:243]
	ds_read_b32 v178, v229 offset:9988
	ds_read_b32 v179, v229 offset:10060
	v_mfma_f32_16x16x4_f32 v[244:247], v97, v217, v[244:247]
	ds_read_b64 v[180:181], v229 offset:9992
	ds_read_b64 v[182:183], v229 offset:10024
	v_mfma_f32_16x16x4_f32 v[240:243], v98, v218, v[240:243]
	ds_read_b64 v[162:163], v228 offset:9984
	ds_read_b64 v[164:165], v228 offset:10016
	v_mfma_f32_16x16x4_f32 v[244:247], v99, v219, v[244:247]
	ds_read_b64 v[166:167], v228 offset:10048
	ds_read_b64 v[168:169], v228 offset:10080
	v_mfma_f32_16x16x4_f32 v[240:243], v100, v220, v[240:243]
	ds_read_b64 v[170:171], v228 offset:9992
	ds_read_b64 v[172:173], v228 offset:10024
	v_mfma_f32_16x16x4_f32 v[244:247], v101, v221, v[244:247]
	ds_read_b64 v[174:175], v228 offset:10056
	ds_read_b64 v[176:177], v228 offset:10088
	v_mfma_f32_16x16x4_f32 v[240:243], v102, v222, v[240:243]
	v_mfma_f32_16x16x4_f32 v[244:247], v103, v223, v[244:247]
	s_waitcnt lgkmcnt(15)
	s_nop 0
	v_mfma_f32_16x16x4_f32 v[208:211], v186, v36, v[208:211]
	s_nop 2
	s_nop 0
	v_pk_add_f32 v[240:241], v[240:241], v[244:245]
	v_pk_add_f32 v[242:243], v[242:243], v[246:247]
	v_fmac_f32_e64 v241, v104, v240
	v_mfma_f32_16x16x4_f32 v[212:215], v190, v36, v[212:215]
	v_pk_fma_f32 v[242:243], v[106:107], v[240:241], v[242:243] op_sel:[0,0,0] op_sel_hi:[1,0,1]
	v_pk_fma_f32 v[242:243], v[108:109], v[240:241], v[242:243] op_sel:[0,1,0] op_sel_hi:[1,1,1]
	v_fmac_f32_e64 v243, v105, v242
	v_mfma_f32_16x16x4_f32 v[216:219], v194, v36, v[216:219]
	ds_bpermute_b32 v204, v232, v240
	ds_bpermute_b32 v205, v232, v241
	ds_bpermute_b32 v206, v232, v242
	v_mfma_f32_16x16x4_f32 v[72:75], v132, v38, 0
	ds_bpermute_b32 v207, v232, v243
	s_waitcnt lgkmcnt(2)
	s_nop 0
	v_pk_fma_f32 v[240:241], v[110:111], v[204:205], v[240:241] op_sel:[0,0,0] op_sel_hi:[1,0,1]
	v_pk_fma_f32 v[240:241], v[112:113], v[204:205], v[240:241] op_sel:[0,1,0] op_sel_hi:[1,1,1]
	v_mfma_f32_16x16x4_f32 v[72:75], v133, v39, v[72:75]
	s_waitcnt lgkmcnt(0)
	s_nop 0
	v_pk_fma_f32 v[240:241], v[114:115], v[206:207], v[240:241] op_sel:[0,0,0] op_sel_hi:[1,0,1]
	v_pk_fma_f32 v[240:241], v[116:117], v[206:207], v[240:241] op_sel:[0,1,0] op_sel_hi:[1,1,1]
	v_pk_fma_f32 v[242:243], v[118:119], v[204:205], v[242:243] op_sel:[0,0,0] op_sel_hi:[1,0,1]
	v_mfma_f32_16x16x4_f32 v[220:223], v198, v36, v[220:223]
	v_pk_fma_f32 v[242:243], v[120:121], v[204:205], v[242:243] op_sel:[0,1,0] op_sel_hi:[1,1,1]
	v_pk_fma_f32 v[242:243], v[122:123], v[206:207], v[242:243] op_sel:[0,0,0] op_sel_hi:[1,0,1]
	v_pk_fma_f32 v[242:243], v[124:125], v[206:207], v[242:243] op_sel:[0,1,0] op_sel_hi:[1,1,1]
	v_mfma_f32_16x16x4_f32 v[208:211], v187, v37, v[208:211]
	v_fmac_f32_e64 v241, v126, v240
	v_pk_fma_f32 v[242:243], v[128:129], v[240:241], v[242:243] op_sel:[0,0,0] op_sel_hi:[1,0,1]
	v_pk_fma_f32 v[242:243], v[130:131], v[240:241], v[242:243] op_sel:[0,1,0] op_sel_hi:[1,1,1]
	v_mfma_f32_16x16x4_f32 v[212:215], v191, v37, v[212:215]
	v_fmac_f32_e32 v243, v127, v242
	v_mov_b32_e32 v252, v240
	v_mov_b32_e64 v253, v241
	v_mfma_f32_16x16x4_f32 v[216:219], v195, v37, v[216:219]
	v_mov_b32_e32 v254, v242
	v_mov_b32_e32 v255, v243
	s_nop 0
	v_permlane32_swap_b32_e32 v252, v254
	v_mfma_f32_16x16x4_f32 v[220:223], v199, v37, v[220:223]
	v_permlane32_swap_b32_e32 v253, v255
	s_nop 0
	v_mfma_f32_16x16x4_f32 v[208:211], v184, v252, v[208:211]
	ds_read_b128 v[88:91], v226
	v_mfma_f32_16x16x4_f32 v[212:215], v188, v252, v[212:215]
	ds_read_b128 v[92:95], v226 offset:64
	v_mfma_f32_16x16x4_f32 v[216:219], v192, v252, v[216:219]
	ds_read_b128 v[96:99], v226 offset:128
	v_mfma_f32_16x16x4_f32 v[220:223], v196, v252, v[220:223]
	ds_read_b128 v[100:103], v226 offset:192
	v_mfma_f32_16x16x4_f32 v[208:211], v185, v253, v[208:211]
	v_mfma_f32_16x16x4_f32 v[212:215], v189, v253, v[212:215]
	v_mfma_f32_16x16x4_f32 v[216:219], v193, v253, v[216:219]
	v_mfma_f32_16x16x4_f32 v[220:223], v197, v253, v[220:223]
	v_mfma_f32_16x16x4_f32 v[248:251], v82, v252, v[240:243]
	v_mfma_f32_16x16x4_f32 v[248:251], v83, v253, v[248:251]
	s_waitcnt lgkmcnt(3)
	s_nop 0
	v_pk_mul_f32 v[208:209], v[208:209], v[88:89]
	v_pk_mul_f32 v[210:211], v[210:211], v[90:91]
	s_nop 0
	s_nop 0
	v_mfma_f32_16x16x4_f32 v[72:75], v140, v208, v[72:75]
	s_waitcnt lgkmcnt(2)
	s_nop 0
	v_pk_mul_f32 v[212:213], v[212:213], v[92:93]
	v_mfma_f32_16x16x4_f32 v[244:247], v141, v209, 0
	v_pk_mul_f32 v[214:215], v[214:215], v[94:95]
	v_mfma_f32_16x16x4_f32 v[72:75], v142, v210, v[72:75]
	s_waitcnt lgkmcnt(1)
	s_nop 0
	v_pk_mul_f32 v[216:217], v[216:217], v[96:97]
	v_mfma_f32_16x16x4_f32 v[244:247], v143, v211, v[244:247]
	v_pk_mul_f32 v[218:219], v[218:219], v[98:99]
	v_mfma_f32_16x16x4_f32 v[72:75], v144, v212, v[72:75]
	s_waitcnt lgkmcnt(0)
	s_nop 0
	v_pk_mul_f32 v[220:221], v[220:221], v[100:101]
	v_mfma_f32_16x16x4_f32 v[244:247], v145, v213, v[244:247]
	v_pk_mul_f32 v[222:223], v[222:223], v[102:103]
	v_mfma_f32_16x16x4_f32 v[72:75], v146, v214, v[72:75]
	s_mov_b64 exec, s[98:99]
	s_nop 0
	ds_write_b32 v231, v248
	ds_write_b32 v231, v249 offset:256
	ds_write_b32 v231, v250 offset:512
	ds_write_b32 v231, v251 offset:768
	s_mov_b64 exec, -1
	s_nop 0
	ds_read_b64 v[186:187], v34 offset:9984
	ds_read_b64 v[190:191], v34 offset:11008
	v_mfma_f32_16x16x4_f32 v[244:247], v147, v215, v[244:247]
	ds_read_b64 v[194:195], v34 offset:12032
	ds_read_b64 v[198:199], v34 offset:13056
	v_mfma_f32_16x16x4_f32 v[72:75], v148, v216, v[72:75]
	ds_read_b64 v[184:185], v236 offset:9984
	ds_read_b64 v[188:189], v236 offset:11008
	ds_read_b64 v[80:81], v32
	v_mfma_f32_16x16x4_f32 v[244:247], v149, v217, v[244:247]
	ds_read_b64 v[82:83], v33
	ds_read_b32 v36, v239 offset:4096
	ds_read_b64 v[192:193], v236 offset:12032
	v_mfma_f32_16x16x4_f32 v[72:75], v150, v218, v[72:75]
	ds_read_b64 v[196:197], v236 offset:13056
	ds_read_b32 v37, v239 offset:4352
	ds_read_b128 v[88:91], v26
	v_mfma_f32_16x16x4_f32 v[244:247], v151, v219, v[244:247]
	ds_read_b128 v[92:95], v26 offset:1024
	ds_read_b128 v[96:99], v26 offset:2048
	ds_read_b128 v[100:103], v26 offset:3072
	v_mfma_f32_16x16x4_f32 v[72:75], v152, v220, v[72:75]
	ds_read_b32 v104, v29 offset:4
	ds_read_b32 v105, v29 offset:76
	ds_read_b64 v[106:107], v29 offset:8
	v_mfma_f32_16x16x4_f32 v[244:247], v153, v221, v[244:247]
	ds_read_b64 v[108:109], v29 offset:40
	ds_read_b32 v126, v31 offset:4
	ds_read_b32 v127, v31 offset:76
	v_mfma_f32_16x16x4_f32 v[72:75], v154, v222, v[72:75]
	ds_read_b64 v[128:129], v31 offset:8
	ds_read_b64 v[130:131], v31 offset:40
	ds_read_b64 v[110:111], v30
	v_mfma_f32_16x16x4_f32 v[244:247], v155, v223, v[244:247]
	ds_read_b64 v[112:113], v30 offset:32
	ds_read_b64 v[114:115], v30 offset:64
	ds_read_b64 v[116:117], v30 offset:96
	ds_read_b64 v[118:119], v30 offset:8
	ds_read_b64 v[120:121], v30 offset:40
	ds_read_b64 v[122:123], v30 offset:72
	ds_read_b64 v[124:125], v30 offset:104
	s_waitcnt lgkmcnt(15)
	s_nop 0
	v_mfma_f32_16x16x4_f32 v[208:211], v186, v38, v[208:211]
	s_nop 1
	s_nop 0
	v_pk_add_f32 v[72:73], v[72:73], v[244:245]
	v_pk_add_f32 v[74:75], v[74:75], v[246:247]
	v_fmac_f32_e64 v73, v156, v72
	v_mfma_f32_16x16x4_f32 v[212:215], v190, v38, v[212:215]
	v_pk_fma_f32 v[74:75], v[158:159], v[72:73], v[74:75] op_sel:[0,0,0] op_sel_hi:[1,0,1]
	v_pk_fma_f32 v[74:75], v[160:161], v[72:73], v[74:75] op_sel:[0,1,0] op_sel_hi:[1,1,1]
	v_fmac_f32_e64 v75, v157, v74
	v_mfma_f32_16x16x4_f32 v[216:219], v194, v38, v[216:219]
	ds_bpermute_b32 v204, v232, v72
	ds_bpermute_b32 v205, v232, v73
	ds_bpermute_b32 v206, v232, v74
	v_mfma_f32_16x16x4_f32 v[240:243], v80, v36, 0
	ds_bpermute_b32 v207, v232, v75
	s_waitcnt lgkmcnt(2)
	s_nop 0
	v_pk_fma_f32 v[72:73], v[162:163], v[204:205], v[72:73] op_sel:[0,0,0] op_sel_hi:[1,0,1]
	v_pk_fma_f32 v[72:73], v[164:165], v[204:205], v[72:73] op_sel:[0,1,0] op_sel_hi:[1,1,1]
	v_mfma_f32_16x16x4_f32 v[240:243], v81, v37, v[240:243]
	s_waitcnt lgkmcnt(0)
	s_nop 0
	v_pk_fma_f32 v[72:73], v[166:167], v[206:207], v[72:73] op_sel:[0,0,0] op_sel_hi:[1,0,1]
	v_pk_fma_f32 v[72:73], v[168:169], v[206:207], v[72:73] op_sel:[0,1,0] op_sel_hi:[1,1,1]
	v_pk_fma_f32 v[74:75], v[170:171], v[204:205], v[74:75] op_sel:[0,0,0] op_sel_hi:[1,0,1]
	v_mfma_f32_16x16x4_f32 v[220:223], v198, v38, v[220:223]
	v_pk_fma_f32 v[74:75], v[172:173], v[204:205], v[74:75] op_sel:[0,1,0] op_sel_hi:[1,1,1]
	v_pk_fma_f32 v[74:75], v[174:175], v[206:207], v[74:75] op_sel:[0,0,0] op_sel_hi:[1,0,1]
	v_pk_fma_f32 v[74:75], v[176:177], v[206:207], v[74:75] op_sel:[0,1,0] op_sel_hi:[1,1,1]
	v_mfma_f32_16x16x4_f32 v[208:211], v187, v39, v[208:211]
	v_fmac_f32_e64 v73, v178, v72
	v_pk_fma_f32 v[74:75], v[180:181], v[72:73], v[74:75] op_sel:[0,0,0] op_sel_hi:[1,0,1]
	v_pk_fma_f32 v[74:75], v[182:183], v[72:73], v[74:75] op_sel:[0,1,0] op_sel_hi:[1,1,1]
	v_mfma_f32_16x16x4_f32 v[212:215], v191, v39, v[212:215]
	v_fmac_f32_e32 v75, v179, v74
	v_mov_b32_e32 v252, v72
	v_mov_b32_e64 v253, v73
	v_mfma_f32_16x16x4_f32 v[216:219], v195, v39, v[216:219]
	v_mov_b32_e32 v254, v74
	v_mov_b32_e32 v255, v75
	s_nop 0
	v_permlane32_swap_b32_e32 v252, v254
	v_mfma_f32_16x16x4_f32 v[220:223], v199, v39, v[220:223]
	v_permlane32_swap_b32_e32 v253, v255
	s_nop 0
	v_mfma_f32_16x16x4_f32 v[208:211], v184, v252, v[208:211]
	ds_read_b128 v[140:143], v226 offset:9984
	v_mfma_f32_16x16x4_f32 v[212:215], v188, v252, v[212:215]
	ds_read_b128 v[144:147], v226 offset:10048
	v_mfma_f32_16x16x4_f32 v[216:219], v192, v252, v[216:219]
	ds_read_b128 v[148:151], v226 offset:10112
	v_mfma_f32_16x16x4_f32 v[220:223], v196, v252, v[220:223]
	ds_read_b128 v[152:155], v226 offset:10176
	v_mfma_f32_16x16x4_f32 v[208:211], v185, v253, v[208:211]
	v_mfma_f32_16x16x4_f32 v[212:215], v189, v253, v[212:215]
	v_mfma_f32_16x16x4_f32 v[216:219], v193, v253, v[216:219]
	v_mfma_f32_16x16x4_f32 v[220:223], v197, v253, v[220:223]
	v_mfma_f32_16x16x4_f32 v[248:251], v134, v252, v[72:75]
	v_mfma_f32_16x16x4_f32 v[248:251], v135, v253, v[248:251]
	s_waitcnt lgkmcnt(3)
	s_nop 0
	v_pk_mul_f32 v[208:209], v[208:209], v[140:141]
	v_pk_mul_f32 v[210:211], v[210:211], v[142:143]
	s_nop 0
	s_nop 0
	v_mfma_f32_16x16x4_f32 v[240:243], v88, v208, v[240:243]
	s_waitcnt lgkmcnt(2)
	s_nop 0
	v_pk_mul_f32 v[212:213], v[212:213], v[144:145]
	v_mfma_f32_16x16x4_f32 v[244:247], v89, v209, 0
	v_pk_mul_f32 v[214:215], v[214:215], v[146:147]
	v_mfma_f32_16x16x4_f32 v[240:243], v90, v210, v[240:243]
	s_waitcnt lgkmcnt(1)
	s_nop 0
	v_pk_mul_f32 v[216:217], v[216:217], v[148:149]
	v_mfma_f32_16x16x4_f32 v[244:247], v91, v211, v[244:247]
	v_pk_mul_f32 v[218:219], v[218:219], v[150:151]
	v_mfma_f32_16x16x4_f32 v[240:243], v92, v212, v[240:243]
	s_waitcnt lgkmcnt(0)
	s_nop 0
	v_pk_mul_f32 v[220:221], v[220:221], v[152:153]
	v_mfma_f32_16x16x4_f32 v[244:247], v93, v213, v[244:247]
	v_pk_mul_f32 v[222:223], v[222:223], v[154:155]
	v_mfma_f32_16x16x4_f32 v[240:243], v94, v214, v[240:243]
	s_mov_b64 exec, s[98:99]
	s_nop 0
	ds_write_b32 v231, v248 offset:2048
	ds_write_b32 v231, v249 offset:2304
	ds_write_b32 v231, v250 offset:2560
	ds_write_b32 v231, v251 offset:2816
	s_mov_b64 exec, -1
	s_nop 0
	ds_read_b64 v[186:187], v35
	ds_read_b64 v[190:191], v35 offset:1024
	v_mfma_f32_16x16x4_f32 v[244:247], v95, v215, v[244:247]
	ds_read_b64 v[194:195], v35 offset:2048
	ds_read_b64 v[198:199], v35 offset:3072
	v_mfma_f32_16x16x4_f32 v[240:243], v96, v216, v[240:243]
	ds_read_b64 v[184:185], v27
	ds_read_b64 v[188:189], v27 offset:1024
	ds_read_b64 v[132:133], v32 offset:9984
	v_mfma_f32_16x16x4_f32 v[244:247], v97, v217, v[244:247]
	ds_read_b64 v[134:135], v33 offset:9984
	ds_read_b32 v38, v239 offset:6144
	ds_read_b64 v[192:193], v27 offset:2048
	v_mfma_f32_16x16x4_f32 v[240:243], v98, v218, v[240:243]
	ds_read_b64 v[196:197], v27 offset:3072
	ds_read_b32 v39, v239 offset:6400
	ds_read_b128 v[140:143], v26 offset:9984
	v_mfma_f32_16x16x4_f32 v[244:247], v99, v219, v[244:247]
	ds_read_b128 v[144:147], v26 offset:11008
	ds_read_b128 v[148:151], v26 offset:12032
	ds_read_b128 v[152:155], v26 offset:13056
	v_mfma_f32_16x16x4_f32 v[240:243], v100, v220, v[240:243]
	ds_read_b32 v156, v29 offset:9988
	ds_read_b32 v157, v29 offset:10060
	ds_read_b64 v[158:159], v29 offset:9992
	v_mfma_f32_16x16x4_f32 v[244:247], v101, v221, v[244:247]
	ds_read_b64 v[160:161], v29 offset:10024
	ds_read_b32 v178, v31 offset:9988
	ds_read_b32 v179, v31 offset:10060
	v_mfma_f32_16x16x4_f32 v[240:243], v102, v222, v[240:243]
	ds_read_b64 v[180:181], v31 offset:9992
	ds_read_b64 v[182:183], v31 offset:10024
	ds_read_b64 v[162:163], v30 offset:9984
	v_mfma_f32_16x16x4_f32 v[244:247], v103, v223, v[244:247]
	ds_read_b64 v[164:165], v30 offset:10016
	ds_read_b64 v[166:167], v30 offset:10048
	ds_read_b64 v[168:169], v30 offset:10080
	ds_read_b64 v[170:171], v30 offset:9992
	ds_read_b64 v[172:173], v30 offset:10024
	ds_read_b64 v[174:175], v30 offset:10056
	ds_read_b64 v[176:177], v30 offset:10088
	s_waitcnt lgkmcnt(15)
	s_nop 0
	v_mfma_f32_16x16x4_f32 v[208:211], v186, v36, v[208:211]
	s_nop 1
	s_nop 0
	v_pk_add_f32 v[240:241], v[240:241], v[244:245]
	v_pk_add_f32 v[242:243], v[242:243], v[246:247]
	v_fmac_f32_e64 v241, v104, v240
	v_mfma_f32_16x16x4_f32 v[212:215], v190, v36, v[212:215]
	v_pk_fma_f32 v[242:243], v[106:107], v[240:241], v[242:243] op_sel:[0,0,0] op_sel_hi:[1,0,1]
	v_pk_fma_f32 v[242:243], v[108:109], v[240:241], v[242:243] op_sel:[0,1,0] op_sel_hi:[1,1,1]
	v_fmac_f32_e64 v243, v105, v242
	v_mfma_f32_16x16x4_f32 v[216:219], v194, v36, v[216:219]
	ds_bpermute_b32 v204, v232, v240
	ds_bpermute_b32 v205, v232, v241
	ds_bpermute_b32 v206, v232, v242
	v_mfma_f32_16x16x4_f32 v[72:75], v132, v38, 0
	ds_bpermute_b32 v207, v232, v243
	s_waitcnt lgkmcnt(2)
	s_nop 0
	v_pk_fma_f32 v[240:241], v[110:111], v[204:205], v[240:241] op_sel:[0,0,0] op_sel_hi:[1,0,1]
	v_pk_fma_f32 v[240:241], v[112:113], v[204:205], v[240:241] op_sel:[0,1,0] op_sel_hi:[1,1,1]
	v_mfma_f32_16x16x4_f32 v[72:75], v133, v39, v[72:75]
	s_waitcnt lgkmcnt(0)
	s_nop 0
	v_pk_fma_f32 v[240:241], v[114:115], v[206:207], v[240:241] op_sel:[0,0,0] op_sel_hi:[1,0,1]
	v_pk_fma_f32 v[240:241], v[116:117], v[206:207], v[240:241] op_sel:[0,1,0] op_sel_hi:[1,1,1]
	v_pk_fma_f32 v[242:243], v[118:119], v[204:205], v[242:243] op_sel:[0,0,0] op_sel_hi:[1,0,1]
	v_mfma_f32_16x16x4_f32 v[220:223], v198, v36, v[220:223]
	v_pk_fma_f32 v[242:243], v[120:121], v[204:205], v[242:243] op_sel:[0,1,0] op_sel_hi:[1,1,1]
	v_pk_fma_f32 v[242:243], v[122:123], v[206:207], v[242:243] op_sel:[0,0,0] op_sel_hi:[1,0,1]
	v_pk_fma_f32 v[242:243], v[124:125], v[206:207], v[242:243] op_sel:[0,1,0] op_sel_hi:[1,1,1]
	v_mfma_f32_16x16x4_f32 v[208:211], v187, v37, v[208:211]
	v_fmac_f32_e64 v241, v126, v240
	v_pk_fma_f32 v[242:243], v[128:129], v[240:241], v[242:243] op_sel:[0,0,0] op_sel_hi:[1,0,1]
	v_pk_fma_f32 v[242:243], v[130:131], v[240:241], v[242:243] op_sel:[0,1,0] op_sel_hi:[1,1,1]
	v_mfma_f32_16x16x4_f32 v[212:215], v191, v37, v[212:215]
	v_fmac_f32_e32 v243, v127, v242
	v_mov_b32_e32 v252, v240
	v_mov_b32_e64 v253, v241
	v_mfma_f32_16x16x4_f32 v[216:219], v195, v37, v[216:219]
	v_mov_b32_e32 v254, v242
	v_mov_b32_e32 v255, v243
	s_nop 0
	v_permlane32_swap_b32_e32 v252, v254
	v_mfma_f32_16x16x4_f32 v[220:223], v199, v37, v[220:223]
	v_permlane32_swap_b32_e32 v253, v255
	s_nop 0
	v_mfma_f32_16x16x4_f32 v[208:211], v184, v252, v[208:211]
	ds_read_b128 v[88:91], v28
	v_mfma_f32_16x16x4_f32 v[212:215], v188, v252, v[212:215]
	ds_read_b128 v[92:95], v28 offset:64
	v_mfma_f32_16x16x4_f32 v[216:219], v192, v252, v[216:219]
	ds_read_b128 v[96:99], v28 offset:128
	v_mfma_f32_16x16x4_f32 v[220:223], v196, v252, v[220:223]
	ds_read_b128 v[100:103], v28 offset:192
	v_mfma_f32_16x16x4_f32 v[208:211], v185, v253, v[208:211]
	v_mfma_f32_16x16x4_f32 v[212:215], v189, v253, v[212:215]
	v_mfma_f32_16x16x4_f32 v[216:219], v193, v253, v[216:219]
	v_mfma_f32_16x16x4_f32 v[220:223], v197, v253, v[220:223]
	v_mfma_f32_16x16x4_f32 v[248:251], v82, v252, v[240:243]
	v_mfma_f32_16x16x4_f32 v[248:251], v83, v253, v[248:251]
	s_waitcnt lgkmcnt(3)
	s_nop 0
	v_pk_mul_f32 v[208:209], v[208:209], v[88:89]
	v_pk_mul_f32 v[210:211], v[210:211], v[90:91]
	s_nop 0
	s_nop 0
	v_mfma_f32_16x16x4_f32 v[72:75], v140, v208, v[72:75]
	s_waitcnt lgkmcnt(2)
	s_nop 0
	v_pk_mul_f32 v[212:213], v[212:213], v[92:93]
	v_mfma_f32_16x16x4_f32 v[244:247], v141, v209, 0
	v_pk_mul_f32 v[214:215], v[214:215], v[94:95]
	v_mfma_f32_16x16x4_f32 v[72:75], v142, v210, v[72:75]
	s_waitcnt lgkmcnt(1)
	s_nop 0
	v_pk_mul_f32 v[216:217], v[216:217], v[96:97]
	v_mfma_f32_16x16x4_f32 v[244:247], v143, v211, v[244:247]
	v_pk_mul_f32 v[218:219], v[218:219], v[98:99]
	v_mfma_f32_16x16x4_f32 v[72:75], v144, v212, v[72:75]
	s_waitcnt lgkmcnt(0)
	s_nop 0
	v_pk_mul_f32 v[220:221], v[220:221], v[100:101]
	v_mfma_f32_16x16x4_f32 v[244:247], v145, v213, v[244:247]
	v_pk_mul_f32 v[222:223], v[222:223], v[102:103]
	v_mfma_f32_16x16x4_f32 v[72:75], v146, v214, v[72:75]
	s_mov_b64 exec, s[98:99]
	s_nop 0
	ds_write_b32 v231, v248 offset:4096
	ds_write_b32 v231, v249 offset:4352
	ds_write_b32 v231, v250 offset:4608
	ds_write_b32 v231, v251 offset:4864
	s_mov_b64 exec, -1
	s_nop 0
	ds_read_b64 v[186:187], v35 offset:9984
	ds_read_b64 v[190:191], v35 offset:11008
	v_mfma_f32_16x16x4_f32 v[244:247], v147, v215, v[244:247]
	ds_read_b64 v[194:195], v35 offset:12032
	ds_read_b64 v[198:199], v35 offset:13056
	v_mfma_f32_16x16x4_f32 v[72:75], v148, v216, v[72:75]
	ds_read_b64 v[184:185], v27 offset:9984
	ds_read_b64 v[188:189], v27 offset:11008
	v_mfma_f32_16x16x4_f32 v[244:247], v149, v217, v[244:247]
	ds_read_b64 v[192:193], v27 offset:12032
	ds_read_b64 v[196:197], v27 offset:13056
	v_mfma_f32_16x16x4_f32 v[72:75], v150, v218, v[72:75]
	v_mfma_f32_16x16x4_f32 v[244:247], v151, v219, v[244:247]
	v_mfma_f32_16x16x4_f32 v[72:75], v152, v220, v[72:75]
	v_mfma_f32_16x16x4_f32 v[244:247], v153, v221, v[244:247]
	v_mfma_f32_16x16x4_f32 v[72:75], v154, v222, v[72:75]
	v_mfma_f32_16x16x4_f32 v[244:247], v155, v223, v[244:247]
	s_waitcnt lgkmcnt(7)
	s_nop 0
	v_mfma_f32_16x16x4_f32 v[208:211], v186, v38, v[208:211]
	s_nop 2
	s_nop 0
	v_pk_add_f32 v[72:73], v[72:73], v[244:245]
	v_pk_add_f32 v[74:75], v[74:75], v[246:247]
	v_fmac_f32_e32 v73, v156, v72
	s_waitcnt lgkmcnt(6)
	v_mfma_f32_16x16x4_f32 v[212:215], v190, v38, v[212:215]
	v_pk_fma_f32 v[74:75], v[158:159], v[72:73], v[74:75] op_sel:[0,0,0] op_sel_hi:[1,0,1]
	v_pk_fma_f32 v[74:75], v[160:161], v[72:73], v[74:75] op_sel:[0,1,0] op_sel_hi:[1,1,1]
	v_fmac_f32_e32 v75, v157, v74
	s_waitcnt lgkmcnt(5)
	v_mfma_f32_16x16x4_f32 v[216:219], v194, v38, v[216:219]
	ds_bpermute_b32 v204, v232, v72
	ds_bpermute_b32 v205, v232, v73
	ds_bpermute_b32 v206, v232, v74
	s_waitcnt lgkmcnt(7)
	s_nop 0
	v_mfma_f32_16x16x4_f32 v[220:223], v198, v38, v[220:223]
	ds_bpermute_b32 v207, v232, v75
	s_waitcnt lgkmcnt(2)
	s_nop 0
	v_pk_fma_f32 v[72:73], v[162:163], v[204:205], v[72:73] op_sel:[0,0,0] op_sel_hi:[1,0,1]
	v_pk_fma_f32 v[72:73], v[164:165], v[204:205], v[72:73] op_sel:[0,1,0] op_sel_hi:[1,1,1]
	v_mfma_f32_16x16x4_f32 v[208:211], v187, v39, v[208:211]
	s_waitcnt lgkmcnt(0)
	s_nop 0
	v_pk_fma_f32 v[72:73], v[166:167], v[206:207], v[72:73] op_sel:[0,0,0] op_sel_hi:[1,0,1]
	v_pk_fma_f32 v[72:73], v[168:169], v[206:207], v[72:73] op_sel:[0,1,0] op_sel_hi:[1,1,1]
	v_pk_fma_f32 v[74:75], v[170:171], v[204:205], v[74:75] op_sel:[0,0,0] op_sel_hi:[1,0,1]
	v_mfma_f32_16x16x4_f32 v[212:215], v191, v39, v[212:215]
	v_pk_fma_f32 v[74:75], v[172:173], v[204:205], v[74:75] op_sel:[0,1,0] op_sel_hi:[1,1,1]
	v_pk_fma_f32 v[74:75], v[174:175], v[206:207], v[74:75] op_sel:[0,0,0] op_sel_hi:[1,0,1]
	v_pk_fma_f32 v[74:75], v[176:177], v[206:207], v[74:75] op_sel:[0,1,0] op_sel_hi:[1,1,1]
	v_mfma_f32_16x16x4_f32 v[216:219], v195, v39, v[216:219]
	v_fmac_f32_e64 v73, v178, v72
	v_pk_fma_f32 v[74:75], v[180:181], v[72:73], v[74:75] op_sel:[0,0,0] op_sel_hi:[1,0,1]
	v_pk_fma_f32 v[74:75], v[182:183], v[72:73], v[74:75] op_sel:[0,1,0] op_sel_hi:[1,1,1]
	v_mfma_f32_16x16x4_f32 v[220:223], v199, v39, v[220:223]
	v_fmac_f32_e32 v75, v179, v74
	v_mov_b32_e32 v252, v72
	v_mov_b32_e32 v253, v73
	v_mov_b32_e32 v254, v74
	v_mov_b32_e32 v255, v75
	s_nop 0
	v_permlane32_swap_b32_e32 v252, v254
	v_permlane32_swap_b32_e32 v253, v255
	s_nop 0
	s_nop 0
	v_mfma_f32_16x16x4_f32 v[208:211], v184, v252, v[208:211]
	ds_read_b128 v[140:143], v28 offset:9984
	v_mfma_f32_16x16x4_f32 v[212:215], v188, v252, v[212:215]
	ds_read_b128 v[144:147], v28 offset:10048
	v_mfma_f32_16x16x4_f32 v[216:219], v192, v252, v[216:219]
	ds_read_b128 v[148:151], v28 offset:10112
	v_mfma_f32_16x16x4_f32 v[220:223], v196, v252, v[220:223]
	ds_read_b128 v[152:155], v28 offset:10176
	v_mfma_f32_16x16x4_f32 v[208:211], v185, v253, v[208:211]
	v_mfma_f32_16x16x4_f32 v[212:215], v189, v253, v[212:215]
	v_mfma_f32_16x16x4_f32 v[216:219], v193, v253, v[216:219]
	v_mfma_f32_16x16x4_f32 v[220:223], v197, v253, v[220:223]
	v_mfma_f32_16x16x4_f32 v[248:251], v134, v252, v[72:75]
	v_mfma_f32_16x16x4_f32 v[248:251], v135, v253, v[248:251]
	s_waitcnt lgkmcnt(3)
	s_nop 0
	v_pk_mul_f32 v[208:209], v[208:209], v[140:141]
	v_pk_mul_f32 v[210:211], v[210:211], v[142:143]
	s_waitcnt lgkmcnt(2)
	s_nop 0
	v_pk_mul_f32 v[212:213], v[212:213], v[144:145]
	v_pk_mul_f32 v[214:215], v[214:215], v[146:147]
	s_waitcnt lgkmcnt(1)
	s_nop 0
	v_pk_mul_f32 v[216:217], v[216:217], v[148:149]
	v_pk_mul_f32 v[218:219], v[218:219], v[150:151]
	s_waitcnt lgkmcnt(0)
	s_nop 0
	v_pk_mul_f32 v[220:221], v[220:221], v[152:153]
	v_pk_mul_f32 v[222:223], v[222:223], v[154:155]
	s_mov_b64 exec, s[98:99]
	s_nop 0
	ds_write_b32 v231, v248 offset:6144
	ds_write_b32 v231, v249 offset:6400
	ds_write_b32 v231, v250 offset:6656
	ds_write_b32 v231, v251 offset:6912
	s_mov_b64 exec, -1
	s_branch .LBB0_655
.Lmy_f_hlp:
	s_setprio 3
	s_cmp_eq_u32 s65, 0
	s_cbranch_scc1 .Lmy_f_nofl
	v_subrev_u32_e32 v70, 16, v70
	v_add_u32_e64 v71, 16, v71
	s_and_b32 s96, s64, 0x800
	v_lshl_add_u32 v21, s96, 2, v68
	v_add_u32_e32 v21, 0xfffff000, v21
	v_cndmask_b32_e64 v76, v71, v70, s[4:5]
	ds_read_b128 v[72:75], v21
	v_ashrrev_i32_e64 v77, 31, v76
	v_lshl_add_u64 v[76:77], v[76:77], 0, s[40:41]
	v_lshlrev_b64 v[76:77], 12, v[76:77]
	v_lshl_add_u64 v[76:77], v[54:55], 0, v[76:77]
	s_waitcnt lgkmcnt(0)
	s_nop 0
	global_store_dwordx4 v[76:77], v[72:75], off
	v_add_u32_e32 v70, 16, v70
	v_subrev_u32_e32 v71, 16, v71

.Lmy_f_hl2:
	s_bfe_u32 s100, s62, 0x20006
	s_lshl_b32 s100, s100, 2
	s_add_i32 s101, s100, -16
	s_add_i32 s100, s100, -12
	s_cmp_lg_u32 s65, 0
	s_cbranch_scc1 .Lmy_f_nol2
	v_add_u32_e32 v70, s101, v70
	v_subrev_u32_e32 v71, s101, v71
	v_add_u32_e32 v21, 64, v70
	v_subrev_u32_e64 v26, 64, v71
	v_cndmask_b32_e64 v32, v26, v21, s[4:5]
	v_ashrrev_i32_e64 v33, 31, v32
	v_lshl_add_u64 v[44:45], v[32:33], 0, s[40:41]
	v_mad_u64_u32 v[46:47], s[96:97], v44, s56, v[50:51]
	v_mad_i32_i24 v47, v45, s56, v47
	v_mov_b32_e32 v166, v46
	v_mov_b32_e32 v167, v47
	global_load_dwordx2 v[26:27], v[46:47], off
	v_mov_b32_e32 v30, v20
	v_mov_b32_e32 v31, v20
	v_cmp_lt_i32_e64 s[96:97], 0, v32
	v_mov_b64_e32 v[28:29], v[30:31]
	s_and_saveexec_b64 s[24:25], s[96:97]
	s_cbranch_execz .Lmy_f_k659
	s_nop 0
	v_add_co_u32_e32 v28, vcc, 0xfffff000, v46
	s_nop 1
	v_addc_co_u32_e32 v29, vcc, -1, v47, vcc
	global_load_dwordx2 v[28:29], v[28:29], off offset:-2048
.Lmy_f_k659:
	s_or_b64 exec, exec, s[24:25]
	s_nop 0
	v_cmp_gt_i32_e64 s[24:25], s3, v32
	s_and_saveexec_b64 s[54:55], s[24:25]
	s_cbranch_execz .Lmy_f_k661
	v_add_co_u32_e32 v30, vcc, 0x1000, v46
	s_nop 1
	v_addc_co_u32_e32 v31, vcc, 0, v47, vcc
	global_load_dwordx2 v[30:31], v[30:31], off offset:2048
.Lmy_f_k661:
	s_or_b64 exec, exec, s[54:55]
	s_nop 0
	global_load_dwordx2 v[32:33], v[46:47], off offset:2048
	v_mov_b32_e32 v21, v20
	v_mov_b64_e32 v[34:35], v[20:21]
	s_and_saveexec_b64 s[54:55], s[96:97]
	s_cbranch_execz .Lmy_f_k663
	global_load_dwordx2 v[34:35], v[46:47], off offset:-4096

.Lmy_f_k665:
	s_or_b64 exec, exec, s[54:55]
	s_nop 0
	v_add_co_u32_e32 v38, vcc, 0x1000, v46
	v_mov_b32_e32 v21, v20
	s_nop 0
	v_addc_co_u32_e32 v39, vcc, 0, v47, vcc
	s_nop 0
	global_load_dwordx2 v[38:39], v[38:39], off
	v_mov_b64_e32 v[40:41], v[20:21]
	s_and_saveexec_b64 s[54:55], s[96:97]
	s_cbranch_execz .Lmy_f_k667
	s_nop 0
	global_load_dwordx2 v[40:41], v[46:47], off offset:-2048

.Lmy_f_k669:
	s_or_b64 exec, exec, s[96:97]
	s_nop 0
	v_lshlrev_b64 v[44:45], 13, v[44:45]
	v_lshl_add_u64 v[44:45], v[52:53], 0, v[44:45]
	v_mov_b32_e32 v170, v44
	v_mov_b32_e32 v171, v45
	v_add_co_u32_e32 v46, vcc, 0x1000, v44
	s_nop 1
	v_addc_co_u32_e32 v47, vcc, 0, v45, vcc
	global_load_dwordx2 v[44:45], v[44:45], off
	s_nop 0
	s_nop 0
	global_load_dwordx2 v[46:47], v[46:47], off
	v_subrev_u32_e32 v70, s101, v70
	v_add_u32_e32 v71, s101, v71
	v_add_u32_e32 v70, s100, v70
	v_subrev_u32_e32 v71, s100, v71
	v_add_u32_e32 v21, 64, v70
	v_subrev_u32_e32 v140, 64, v71
	v_cndmask_b32_e64 v146, v140, v21, s[4:5]
	v_ashrrev_i32_e64 v147, 31, v146
	v_lshl_add_u64 v[158:159], v[146:147], 0, s[40:41]
	v_mad_u64_u32 v[160:161], s[96:97], v158, s56, v[50:51]
	v_mad_i32_i24 v161, v159, s56, v161
	v_mov_b32_e32 v174, v160
	v_mov_b32_e32 v175, v161
	global_load_dwordx2 v[140:141], v[160:161], off
	v_mov_b32_e32 v144, v20
	v_mov_b32_e32 v145, v20
	v_cmp_lt_i32_e64 s[96:97], 0, v146
	v_mov_b64_e32 v[142:143], v[144:145]
	s_and_saveexec_b64 s[24:25], s[96:97]
	s_cbranch_execz .Lmy_f_l659
	s_nop 0
	v_add_co_u32_e32 v142, vcc, 0xfffff000, v160
	s_nop 1
	v_addc_co_u32_e32 v143, vcc, -1, v161, vcc
	global_load_dwordx2 v[142:143], v[142:143], off offset:-2048
.Lmy_f_l659:
	s_or_b64 exec, exec, s[24:25]
	s_nop 0
	v_cmp_gt_i32_e64 s[24:25], s3, v146
	s_and_saveexec_b64 s[54:55], s[24:25]
	s_cbranch_execz .Lmy_f_l661
	v_add_co_u32_e32 v144, vcc, 0x1000, v160
	s_nop 1
	v_addc_co_u32_e32 v145, vcc, 0, v161, vcc
	global_load_dwordx2 v[144:145], v[144:145], off offset:2048
.Lmy_f_l661:
	s_or_b64 exec, exec, s[54:55]
	s_nop 0
	global_load_dwordx2 v[146:147], v[160:161], off offset:2048
	v_mov_b32_e32 v21, v20
	v_mov_b64_e32 v[148:149], v[20:21]
	s_and_saveexec_b64 s[54:55], s[96:97]
	s_cbranch_execz .Lmy_f_l663
	global_load_dwordx2 v[148:149], v[160:161], off offset:-4096

.Lmy_f_l665:
	s_or_b64 exec, exec, s[54:55]
	s_nop 0
	v_add_co_u32_e32 v152, vcc, 0x1000, v160
	v_mov_b32_e32 v21, v20
	s_nop 0
	v_addc_co_u32_e32 v153, vcc, 0, v161, vcc
	s_nop 0
	global_load_dwordx2 v[152:153], v[152:153], off
	v_mov_b64_e32 v[154:155], v[20:21]
	s_and_saveexec_b64 s[54:55], s[96:97]
	s_cbranch_execz .Lmy_f_l667
	s_nop 0
	global_load_dwordx2 v[154:155], v[160:161], off offset:-2048

.Lmy_f_l669:
	s_or_b64 exec, exec, s[96:97]
	s_nop 0
	v_lshlrev_b64 v[158:159], 13, v[158:159]
	v_lshl_add_u64 v[158:159], v[52:53], 0, v[158:159]
	v_mov_b32_e32 v178, v158
	v_mov_b32_e32 v179, v159
	v_add_co_u32_e32 v160, vcc, 0x1000, v158
	s_nop 1
	v_addc_co_u32_e32 v161, vcc, 0, v159, vcc
	global_load_dwordx2 v[158:159], v[158:159], off
	s_nop 0
	s_nop 0
	global_load_dwordx2 v[160:161], v[160:161], off
	v_subrev_u32_e32 v70, s100, v70
	v_add_u32_e32 v71, s100, v71
	s_mov_b32 s96, 0xffffe000
	s_mov_b32 s97, -1
	s_nop 0
	v_lshl_add_u64 v[164:165], v[166:167], 0, s[96:97]
	v_lshl_add_u64 v[172:173], v[174:175], 0, s[96:97]
	s_mov_b32 s96, 0x2000
	s_mov_b32 s97, 0
	s_nop 0
	v_lshl_add_u64 v[168:169], v[166:167], 0, s[96:97]
	v_lshl_add_u64 v[176:177], v[174:175], 0, s[96:97]
	s_mov_b32 s96, 0x800
	v_lshl_add_u64 v[170:171], v[170:171], 0, s[96:97]
	v_lshl_add_u64 v[178:179], v[178:179], 0, s[96:97]
.Lmy_f_nol2:
	s_lshl_b32 s96, s101, 8
	v_add_u32_e32 v67, s96, v67
	s_andn2_b64 vcc, exec, s[50:51]
	s_cbranch_vccnz .LBB0_655
	s_waitcnt vmcnt(15)
	v_lshlrev_b32_e32 v72, 16, v28
	v_and_b32_e32 v73, 0xffff0000, v28
	v_lshlrev_b32_e64 v76, 16, v30
	v_and_b32_e32 v77, 0xffff0000, v30
	v_lshlrev_b32_e64 v74, 16, v26
	v_and_b32_e32 v75, 0xffff0000, v26
	v_pk_add_f32 v[72:73], v[72:73], v[76:77]
	s_waitcnt vmcnt(13)
	v_lshlrev_b32_e32 v78, 16, v42
	v_pk_fma_f32 v[72:73], v[72:73], 0.5, v[74:75] op_sel_hi:[1,0,1] neg_lo:[0,0,1] neg_hi:[0,0,1]
	v_and_b32_e32 v79, 0xffff0000, v42
	v_pk_fma_f32 v[72:73], v[0:1], v[72:73], v[74:75]
	v_lshlrev_b32_e64 v74, 16, v40
	v_and_b32_e32 v75, 0xffff0000, v40
	v_lshlrev_b32_e64 v76, 16, v38
	v_and_b32_e32 v77, 0xffff0000, v38
	v_pk_add_f32 v[74:75], v[74:75], v[78:79]
	s_waitcnt vmcnt(12)
	v_cvt_f32_f16_e32 v21, v44
	v_pk_fma_f32 v[74:75], v[74:75], 0.5, v[76:77] op_sel_hi:[1,0,1] neg_lo:[0,0,1] neg_hi:[0,0,1]
	v_lshlrev_b32_e64 v80, 16, v31
	v_pk_fma_f32 v[76:77], v[8:9], v[74:75], v[76:77]
	v_lshlrev_b32_e64 v74, 16, v29
	v_and_b32_e32 v75, 0xffff0000, v29
	v_and_b32_e32 v81, 0xffff0000, v31
	v_lshlrev_b32_e64 v78, 16, v27
	v_and_b32_e32 v79, 0xffff0000, v27
	v_pk_add_f32 v[74:75], v[74:75], v[80:81]
	v_cvt_f32_f16_sdwa v84, v44 dst_sel:DWORD dst_unused:UNUSED_PAD src0_sel:WORD_1
	v_pk_fma_f32 v[74:75], v[74:75], 0.5, v[78:79] op_sel_hi:[1,0,1] neg_lo:[0,0,1] neg_hi:[0,0,1]
	v_lshlrev_b32_e64 v82, 16, v43
	v_pk_fma_f32 v[74:75], v[2:3], v[74:75], v[78:79]
	v_lshlrev_b32_e64 v78, 16, v41
	v_and_b32_e32 v79, 0xffff0000, v41
	v_and_b32_e32 v83, 0xffff0000, v43
	v_cvt_f32_f16_e32 v88, v45
	v_lshlrev_b32_e32 v80, 16, v39
	v_and_b32_e32 v81, 0xffff0000, v39
	v_pk_add_f32 v[78:79], v[78:79], v[82:83]
	v_mul_f32_e32 v21, 0xbf1b4598, v21
	v_pk_fma_f32 v[78:79], v[78:79], 0.5, v[80:81] op_sel_hi:[1,0,1] neg_lo:[0,0,1] neg_hi:[0,0,1]
	v_mul_f32_e32 v21, 0x3fb8aa3b, v21
	v_cvt_f32_f16_sdwa v89, v45 dst_sel:DWORD dst_unused:UNUSED_PAD src0_sel:WORD_1
	v_pk_fma_f32 v[78:79], v[10:11], v[78:79], v[80:81]
	v_exp_f32_e64 v80, v21
	v_mul_f32_e32 v21, 0xbf1b4598, v84
	v_mul_f32_e32 v21, 0x3fb8aa3b, v21
	v_lshlrev_b32_e64 v82, 16, v34
	v_and_b32_e32 v83, 0xffff0000, v34
	v_lshlrev_b32_e64 v86, 16, v36
	v_and_b32_e32 v87, 0xffff0000, v36
	v_exp_f32_e32 v81, v21
	v_lshlrev_b32_e32 v84, 16, v32
	v_and_b32_e32 v85, 0xffff0000, v32
	v_pk_add_f32 v[82:83], v[82:83], v[86:87]
	v_mul_f32_e32 v21, 0xbf1b4598, v88
	v_pk_fma_f32 v[82:83], v[82:83], 0.5, v[84:85] op_sel_hi:[1,0,1] neg_lo:[0,0,1] neg_hi:[0,0,1]
	v_mul_f32_e32 v21, 0x3fb8aa3b, v21
	v_pk_fma_f32 v[96:97], v[4:5], v[82:83], v[84:85]
	v_exp_f32_e64 v82, v21
	v_mul_f32_e32 v21, 0xbf1b4598, v89
	v_lshlrev_b32_e64 v84, 16, v35
	v_and_b32_e32 v85, 0xffff0000, v35
	v_lshlrev_b32_e64 v88, 16, v37
	v_and_b32_e32 v89, 0xffff0000, v37
	v_lshlrev_b32_e64 v86, 16, v33
	v_and_b32_e32 v87, 0xffff0000, v33
	v_pk_add_f32 v[84:85], v[84:85], v[88:89]
	s_waitcnt vmcnt(11)
	s_nop 0
	v_cvt_f32_f16_sdwa v93, v46 dst_sel:DWORD dst_unused:UNUSED_PAD src0_sel:WORD_1
	v_pk_fma_f32 v[84:85], v[84:85], 0.5, v[86:87] op_sel_hi:[1,0,1] neg_lo:[0,0,1] neg_hi:[0,0,1]
	v_cvt_f32_f16_e32 v92, v46
	s_nop 0
	v_pk_fma_f32 v[94:95], v[6:7], v[84:85], v[86:87]
	v_pk_mul_f32 v[84:85], v[12:13], v[96:97]
	v_pk_mul_f32 v[88:89], v[14:15], v[94:95]
	v_pk_mul_f32 v[86:87], v[84:85], v[84:85]
	v_pk_mul_f32 v[90:91], v[88:89], v[88:89]
	v_add_f32_e32 v83, v86, v87
	v_add_f32_e32 v83, v90, v83
	v_add_f32_e64 v83, v91, v83
	v_cvt_f32_f16_sdwa v99, v47 dst_sel:DWORD dst_unused:UNUSED_PAD src0_sel:WORD_1
	v_cvt_f32_f16_e32 v98, v47
	s_nop 0
	v_add_f32_dpp v83, v83, v83 quad_perm:[1,0,3,2] row_mask:0xf bank_mask:0xf bound_ctrl:1
	v_mul_f32_e32 v21, 0x3fb8aa3b, v21
	s_bitcmp1_b32 s22, 0
	s_nop 0
	v_add_f32_dpp v83, v83, v83 quad_perm:[2,3,0,1] row_mask:0xf bank_mask:0xf bound_ctrl:1
	s_cselect_b32 s23, 0x2000, 0
	s_nop 0
	s_nop 0
	v_add_f32_dpp v83, v83, v83 row_half_mirror row_mask:0xf bank_mask:0xf bound_ctrl:1
	s_nop 1
	s_nop 0
	v_add_f32_dpp v83, v83, v83 row_mirror row_mask:0xf bank_mask:0xf bound_ctrl:1
	v_max_f32_e32 v83, 0x179abe15, v83
	v_rsq_f32_e32 v86, v83
	v_exp_f32_e32 v83, v21
	v_add_u32_e64 v21, s23, v67
	v_pk_mul_f32 v[90:91], v[84:85], v[86:87] op_sel_hi:[1,0]
	v_pk_mul_f32 v[100:101], v[88:89], v[86:87] op_sel_hi:[1,0]
	v_xor_b32_e32 v85, 0x80000000, v91
	v_xor_b32_e32 v84, 0x80000000, v90
	v_pk_mul_f32 v[88:89], v[90:91], v[92:93]
	v_pk_mul_f32 v[90:91], v[100:101], v[98:99]
	v_pk_add_f32 v[92:93], v[92:93], -1.0 op_sel_hi:[1,0]
	v_pk_add_f32 v[98:99], v[98:99], -1.0 op_sel_hi:[1,0]
	v_pk_fma_f32 v[92:93], v[16:17], v[92:93], 1.0 op_sel_hi:[1,1,0]
	v_pk_fma_f32 v[98:99], v[18:19], v[98:99], 1.0 op_sel_hi:[1,1,0]
	v_xor_b32_e32 v86, 0x80000000, v100
	v_xor_b32_e32 v87, 0x80000000, v101
	v_pk_mul_f32 v[94:95], v[94:95], v[98:99]
	v_pk_mul_f32 v[92:93], v[96:97], v[92:93]
	ds_write_b128 v67, v[80:83]
	ds_write_b128 v67, v[84:87] offset:8192
	ds_write_b128 v67, v[88:91] offset:16384
	ds_write_b128 v67, v[92:95] offset:24576
	ds_write_b128 v67, v[72:75] offset:32768
	ds_write_b128 v21, v[76:79] offset:40960
	v_add_u32_e32 v67, 0x400, v67
	s_waitcnt vmcnt(0)
	v_lshlrev_b32_e32 v72, 16, v142
	v_and_b32_e32 v73, 0xffff0000, v142
	v_lshlrev_b32_e64 v76, 16, v144
	v_and_b32_e32 v77, 0xffff0000, v144
	v_lshlrev_b32_e64 v74, 16, v140
	v_and_b32_e32 v75, 0xffff0000, v140
	v_pk_add_f32 v[72:73], v[72:73], v[76:77]
	s_waitcnt vmcnt(2)
	v_lshlrev_b32_e32 v78, 16, v156
	v_pk_fma_f32 v[72:73], v[72:73], 0.5, v[74:75] op_sel_hi:[1,0,1] neg_lo:[0,0,1] neg_hi:[0,0,1]
	v_and_b32_e32 v79, 0xffff0000, v156
	v_pk_fma_f32 v[72:73], v[0:1], v[72:73], v[74:75]
	v_lshlrev_b32_e64 v74, 16, v154
	v_and_b32_e32 v75, 0xffff0000, v154
	v_lshlrev_b32_e64 v76, 16, v152
	v_and_b32_e32 v77, 0xffff0000, v152
	v_pk_add_f32 v[74:75], v[74:75], v[78:79]
	s_waitcnt vmcnt(1)
	v_cvt_f32_f16_e32 v21, v158
	v_pk_fma_f32 v[74:75], v[74:75], 0.5, v[76:77] op_sel_hi:[1,0,1] neg_lo:[0,0,1] neg_hi:[0,0,1]
	v_lshlrev_b32_e64 v80, 16, v145
	v_pk_fma_f32 v[76:77], v[8:9], v[74:75], v[76:77]
	v_lshlrev_b32_e64 v74, 16, v143
	v_and_b32_e32 v75, 0xffff0000, v143
	v_and_b32_e32 v81, 0xffff0000, v145
	v_lshlrev_b32_e64 v78, 16, v141
	v_and_b32_e32 v79, 0xffff0000, v141
	v_pk_add_f32 v[74:75], v[74:75], v[80:81]
	v_cvt_f32_f16_sdwa v84, v158 dst_sel:DWORD dst_unused:UNUSED_PAD src0_sel:WORD_1
	v_pk_fma_f32 v[74:75], v[74:75], 0.5, v[78:79] op_sel_hi:[1,0,1] neg_lo:[0,0,1] neg_hi:[0,0,1]
	v_lshlrev_b32_e64 v82, 16, v157
	v_pk_fma_f32 v[74:75], v[2:3], v[74:75], v[78:79]
	v_lshlrev_b32_e64 v78, 16, v155
	v_and_b32_e32 v79, 0xffff0000, v155
	v_and_b32_e32 v83, 0xffff0000, v157
	v_cvt_f32_f16_e32 v88, v159
	v_lshlrev_b32_e32 v80, 16, v153
	v_and_b32_e32 v81, 0xffff0000, v153
	v_pk_add_f32 v[78:79], v[78:79], v[82:83]
	v_mul_f32_e32 v21, 0xbf1b4598, v21
	v_pk_fma_f32 v[78:79], v[78:79], 0.5, v[80:81] op_sel_hi:[1,0,1] neg_lo:[0,0,1] neg_hi:[0,0,1]
	v_mul_f32_e32 v21, 0x3fb8aa3b, v21
	v_cvt_f32_f16_sdwa v89, v159 dst_sel:DWORD dst_unused:UNUSED_PAD src0_sel:WORD_1
	v_pk_fma_f32 v[78:79], v[10:11], v[78:79], v[80:81]
	v_exp_f32_e64 v80, v21
	v_mul_f32_e32 v21, 0xbf1b4598, v84
	v_mul_f32_e32 v21, 0x3fb8aa3b, v21
	v_lshlrev_b32_e64 v82, 16, v148
	v_and_b32_e32 v83, 0xffff0000, v148
	v_lshlrev_b32_e64 v86, 16, v150
	v_and_b32_e32 v87, 0xffff0000, v150
	v_exp_f32_e32 v81, v21
	v_lshlrev_b32_e32 v84, 16, v146
	v_and_b32_e32 v85, 0xffff0000, v146
	v_pk_add_f32 v[82:83], v[82:83], v[86:87]
	v_mul_f32_e32 v21, 0xbf1b4598, v88
	v_pk_fma_f32 v[82:83], v[82:83], 0.5, v[84:85] op_sel_hi:[1,0,1] neg_lo:[0,0,1] neg_hi:[0,0,1]
	v_mul_f32_e32 v21, 0x3fb8aa3b, v21
	v_pk_fma_f32 v[96:97], v[4:5], v[82:83], v[84:85]
	v_exp_f32_e64 v82, v21
	v_mul_f32_e32 v21, 0xbf1b4598, v89
	v_lshlrev_b32_e64 v84, 16, v149
	v_and_b32_e32 v85, 0xffff0000, v149
	v_lshlrev_b32_e64 v88, 16, v151
	v_and_b32_e32 v89, 0xffff0000, v151
	v_lshlrev_b32_e64 v86, 16, v147
	v_and_b32_e32 v87, 0xffff0000, v147
	v_pk_add_f32 v[84:85], v[84:85], v[88:89]
	s_waitcnt vmcnt(0)
	s_nop 0
	v_cvt_f32_f16_sdwa v93, v160 dst_sel:DWORD dst_unused:UNUSED_PAD src0_sel:WORD_1
	v_pk_fma_f32 v[84:85], v[84:85], 0.5, v[86:87] op_sel_hi:[1,0,1] neg_lo:[0,0,1] neg_hi:[0,0,1]
	v_cvt_f32_f16_e32 v92, v160
	s_nop 0
	v_pk_fma_f32 v[94:95], v[6:7], v[84:85], v[86:87]
	v_pk_mul_f32 v[84:85], v[12:13], v[96:97]
	v_pk_mul_f32 v[88:89], v[14:15], v[94:95]
	v_pk_mul_f32 v[86:87], v[84:85], v[84:85]
	v_pk_mul_f32 v[90:91], v[88:89], v[88:89]
	v_add_f32_e32 v83, v86, v87
	v_add_f32_e32 v83, v90, v83
	v_add_f32_e64 v83, v91, v83
	v_cvt_f32_f16_sdwa v99, v161 dst_sel:DWORD dst_unused:UNUSED_PAD src0_sel:WORD_1
	v_cvt_f32_f16_e32 v98, v161
	s_nop 0
	v_add_f32_dpp v83, v83, v83 quad_perm:[1,0,3,2] row_mask:0xf bank_mask:0xf bound_ctrl:1
	v_mul_f32_e32 v21, 0x3fb8aa3b, v21
	s_bitcmp1_b32 s22, 0
	s_nop 0
	v_add_f32_dpp v83, v83, v83 quad_perm:[2,3,0,1] row_mask:0xf bank_mask:0xf bound_ctrl:1
	s_cselect_b32 s23, 0x2000, 0
	s_nop 0
	s_nop 0
	v_add_f32_dpp v83, v83, v83 row_half_mirror row_mask:0xf bank_mask:0xf bound_ctrl:1
	s_nop 1
	s_nop 0
	v_add_f32_dpp v83, v83, v83 row_mirror row_mask:0xf bank_mask:0xf bound_ctrl:1
	v_max_f32_e32 v83, 0x179abe15, v83
	v_rsq_f32_e32 v86, v83
	v_exp_f32_e32 v83, v21
	v_add_u32_e64 v21, s23, v67
	v_pk_mul_f32 v[90:91], v[84:85], v[86:87] op_sel_hi:[1,0]
	v_pk_mul_f32 v[100:101], v[88:89], v[86:87] op_sel_hi:[1,0]
	v_xor_b32_e32 v85, 0x80000000, v91
	v_xor_b32_e32 v84, 0x80000000, v90
	v_pk_mul_f32 v[88:89], v[90:91], v[92:93]
	v_pk_mul_f32 v[90:91], v[100:101], v[98:99]
	v_pk_add_f32 v[92:93], v[92:93], -1.0 op_sel_hi:[1,0]
	v_pk_add_f32 v[98:99], v[98:99], -1.0 op_sel_hi:[1,0]
	v_pk_fma_f32 v[92:93], v[16:17], v[92:93], 1.0 op_sel_hi:[1,1,0]
	v_pk_fma_f32 v[98:99], v[18:19], v[98:99], 1.0 op_sel_hi:[1,1,0]
	v_xor_b32_e32 v86, 0x80000000, v100
	v_xor_b32_e32 v87, 0x80000000, v101
	v_pk_mul_f32 v[94:95], v[94:95], v[98:99]
	v_pk_mul_f32 v[92:93], v[96:97], v[92:93]
	ds_write_b128 v67, v[80:83]
	ds_write_b128 v67, v[84:87] offset:8192
	ds_write_b128 v67, v[88:91] offset:16384
	ds_write_b128 v67, v[92:95] offset:24576
	ds_write_b128 v67, v[72:75] offset:32768
	ds_write_b128 v21, v[76:79] offset:40960
	s_lshl_b32 s96, s100, 8
	v_subrev_u32_e32 v67, s96, v67
	s_cmp_gt_u32 s65, 61
	s_cbranch_scc1 .Lmy_f_nol34
	s_cmp_eq_u32 s65, 61
	s_cbranch_scc1 .Lmy_f_slow34
	s_cmp_lg_u32 s4, 0
	s_nop 0
	s_mov_b32 s100, 0xfffd0000
	s_cselect_b32 s100, 0x30000, s100
	s_cselect_b32 s101, 0, -1
	s_nop 0
	s_mov_b32 s96, 0xfffc0000
	s_cselect_b32 s96, 0x40000, s96
	s_cselect_b32 s97, 0, -1
	s_nop 0
	v_lshl_add_u64 v[166:167], v[166:167], 0, s[100:101]
	v_lshl_add_u64 v[164:165], v[164:165], 0, s[100:101]
	v_lshl_add_u64 v[168:169], v[168:169], 0, s[100:101]
	v_lshl_add_u64 v[170:171], v[170:171], 0, s[96:97]
	global_load_dwordx2 v[26:27], v[166:167], off
	global_load_dwordx2 v[28:29], v[164:165], off offset:2048
	global_load_dwordx2 v[30:31], v[168:169], off offset:-2048
	global_load_dwordx2 v[32:33], v[166:167], off offset:2048
	global_load_dwordx2 v[34:35], v[166:167], off offset:-4096
	global_load_dwordx2 v[36:37], v[168:169], off
	global_load_dwordx2 v[38:39], v[168:169], off offset:-4096
	global_load_dwordx2 v[40:41], v[166:167], off offset:-2048
	global_load_dwordx2 v[42:43], v[168:169], off offset:2048
	global_load_dwordx2 v[44:45], v[170:171], off offset:-2048
	global_load_dwordx2 v[46:47], v[170:171], off offset:2048
	v_lshl_add_u64 v[174:175], v[174:175], 0, s[100:101]
	v_lshl_add_u64 v[172:173], v[172:173], 0, s[100:101]
	v_lshl_add_u64 v[176:177], v[176:177], 0, s[100:101]
	v_lshl_add_u64 v[178:179], v[178:179], 0, s[96:97]
	global_load_dwordx2 v[140:141], v[174:175], off
	global_load_dwordx2 v[142:143], v[172:173], off offset:2048
	global_load_dwordx2 v[144:145], v[176:177], off offset:-2048
	global_load_dwordx2 v[146:147], v[174:175], off offset:2048
	global_load_dwordx2 v[148:149], v[174:175], off offset:-4096
	global_load_dwordx2 v[150:151], v[176:177], off
	global_load_dwordx2 v[152:153], v[176:177], off offset:-4096
	global_load_dwordx2 v[154:155], v[174:175], off offset:-2048
	global_load_dwordx2 v[156:157], v[176:177], off offset:2048
	global_load_dwordx2 v[158:159], v[178:179], off offset:-2048
	global_load_dwordx2 v[160:161], v[178:179], off offset:2048
	s_branch .Lmy_f_nol34
.Lmy_f_slow34:
	s_add_i32 s101, s101, 32
	s_add_i32 s100, s100, 32
	v_add_u32_e32 v70, s101, v70
	v_subrev_u32_e32 v71, s101, v71
	v_add_u32_e32 v21, 64, v70
	v_subrev_u32_e64 v26, 64, v71
	v_cndmask_b32_e64 v32, v26, v21, s[4:5]
	v_ashrrev_i32_e64 v33, 31, v32
	v_lshl_add_u64 v[44:45], v[32:33], 0, s[40:41]
	v_mad_u64_u32 v[46:47], s[96:97], v44, s56, v[50:51]
	v_mad_i32_i24 v47, v45, s56, v47
	global_load_dwordx2 v[26:27], v[46:47], off
	v_mov_b32_e32 v30, v20
	v_mov_b32_e32 v31, v20
	v_cmp_lt_i32_e64 s[96:97], 0, v32
	v_mov_b64_e32 v[28:29], v[30:31]
	s_and_saveexec_b64 s[24:25], s[96:97]
	s_cbranch_execz .Lmy_f_m659
	s_nop 0
	v_add_co_u32_e32 v28, vcc, 0xfffff000, v46
	s_nop 1
	v_addc_co_u32_e32 v29, vcc, -1, v47, vcc
	global_load_dwordx2 v[28:29], v[28:29], off offset:-2048

.Lmy_f_m669:
	s_or_b64 exec, exec, s[96:97]
	s_nop 0
	v_lshlrev_b64 v[44:45], 13, v[44:45]
	v_lshl_add_u64 v[44:45], v[52:53], 0, v[44:45]
	v_add_co_u32_e32 v46, vcc, 0x1000, v44
	s_nop 1
	v_addc_co_u32_e32 v47, vcc, 0, v45, vcc
	global_load_dwordx2 v[44:45], v[44:45], off
	s_nop 0
	s_nop 0
	global_load_dwordx2 v[46:47], v[46:47], off
	v_subrev_u32_e32 v70, s101, v70
	v_add_u32_e32 v71, s101, v71
	v_add_u32_e32 v70, s100, v70
	v_subrev_u32_e32 v71, s100, v71
	v_add_u32_e32 v21, 64, v70
	v_subrev_u32_e32 v140, 64, v71
	v_cndmask_b32_e64 v146, v140, v21, s[4:5]
	v_ashrrev_i32_e64 v147, 31, v146
	v_lshl_add_u64 v[158:159], v[146:147], 0, s[40:41]
	v_mad_u64_u32 v[160:161], s[96:97], v158, s56, v[50:51]
	v_mad_i32_i24 v161, v159, s56, v161
	global_load_dwordx2 v[140:141], v[160:161], off
	v_mov_b32_e32 v144, v20
	v_mov_b32_e32 v145, v20
	v_cmp_lt_i32_e64 s[96:97], 0, v146
	v_mov_b64_e32 v[142:143], v[144:145]
	s_and_saveexec_b64 s[24:25], s[96:97]
	s_cbranch_execz .Lmy_f_n659
	s_nop 0
	v_add_co_u32_e32 v142, vcc, 0xfffff000, v160
	s_nop 1
	v_addc_co_u32_e32 v143, vcc, -1, v161, vcc
	global_load_dwordx2 v[142:143], v[142:143], off offset:-2048

.Lmy_f_n669:
	s_or_b64 exec, exec, s[96:97]
	s_nop 0
	v_lshlrev_b64 v[158:159], 13, v[158:159]
	v_lshl_add_u64 v[158:159], v[52:53], 0, v[158:159]
	v_add_co_u32_e32 v160, vcc, 0x1000, v158
	s_nop 1
	v_addc_co_u32_e32 v161, vcc, 0, v159, vcc
	global_load_dwordx2 v[158:159], v[158:159], off
	s_nop 0
	s_nop 0
	global_load_dwordx2 v[160:161], v[160:161], off
	v_subrev_u32_e32 v70, s100, v70
	v_add_u32_e32 v71, s100, v71
.Lmy_f_nol34:
	s_waitcnt lgkmcnt(0)
	s_nop 0
	s_bfe_u32 s96, s62, 0x20006
	s_lshl_b32 s100, s96, 11
	s_nop 0
	v_lshl_add_u32 v72, v224, 2, s100
	s_and_b32 s97, s96, 1
	s_nop 0
	s_mul_i32 s97, s97, 0x2700
	s_mov_b32 s101, 0x1c000
	s_mov_b32 s100, 0x6100
	s_bitcmp0_b32 s65, 0
	s_nop 0
	s_cselect_b32 s101, 0xe000, s101
	s_cselect_b32 s100, 0x4e00, s100
	s_cmp_gt_u32 s96, 1
	s_cselect_b32 s100, s100, 0
	s_add_i32 s97, s97, s101
	s_add_i32 s97, s97, s100
	ds_read_b32 v80, v72
	ds_read_b32 v81, v72 offset:256
	ds_read_b32 v82, v72 offset:512
	ds_read_b32 v83, v72 offset:768
	ds_read_b32 v84, v72 offset:1024
	ds_read_b32 v85, v72 offset:1280
	ds_read_b32 v86, v72 offset:1536
	ds_read_b32 v87, v72 offset:1792
	ds_read_b32 v88, v72 offset:8192
	ds_read_b32 v89, v72 offset:8448
	ds_read_b32 v90, v72 offset:8704
	ds_read_b32 v91, v72 offset:8960
	ds_read_b32 v92, v72 offset:9216
	ds_read_b32 v93, v72 offset:9472
	ds_read_b32 v94, v72 offset:9728
	ds_read_b32 v95, v72 offset:9984
	ds_read_b32 v96, v72 offset:32768
	ds_read_b32 v97, v72 offset:33024
	ds_read_b32 v98, v72 offset:33280
	ds_read_b32 v99, v72 offset:33536
	ds_read_b32 v100, v72 offset:33792
	ds_read_b32 v101, v72 offset:34048
	ds_read_b32 v102, v72 offset:34304
	ds_read_b32 v103, v72 offset:34560
	v_and_b32_e64 v74, 3, v224
	v_bfe_u32 v75, v224, 2, 2
	v_lshrrev_b32_e32 v76, 4, v224
	v_lshlrev_b32_e32 v74, 2, v74
	v_lshl_add_u32 v74, v75, 8, v74
	v_lshl_add_u32 v74, v76, 10, v74
	s_add_i32 s100, s97, 0x0
	v_add_u32_e32 v74, s100, v74
	v_xor_b32_e32 v76, 0, v75
	v_xor_b32_e32 v77, 1, v75
	v_xor_b32_e32 v78, 2, v75
	v_xor_b32_e32 v79, 3, v75
	v_lshl_add_u32 v76, v76, 4, v74
	v_lshl_add_u32 v77, v77, 4, v74
	v_lshl_add_u32 v78, v78, 4, v74
	v_lshl_add_u32 v79, v79, 4, v74
	s_waitcnt lgkmcnt(15)
	v_mov_b32_e32 v104, v80
	v_mul_f32_e32 v105, v104, v81
	v_mul_f32_e32 v106, v105, v82
	v_mul_f32_e32 v107, v106, v83
	v_mul_f32_e32 v108, v107, v84
	v_mul_f32_e32 v109, v108, v85
	v_mul_f32_e32 v110, v109, v86
	v_mul_f32_e32 v111, v110, v87
	v_mov_b32_e32 v112, v88
	s_waitcnt lgkmcnt(14)
	v_mul_f32_e32 v113, v104, v89
	s_waitcnt lgkmcnt(13)
	v_mul_f32_e32 v114, v105, v90
	s_waitcnt lgkmcnt(12)
	v_mul_f32_e32 v115, v106, v91
	s_waitcnt lgkmcnt(11)
	v_mul_f32_e32 v116, v107, v92
	s_waitcnt lgkmcnt(10)
	v_mul_f32_e32 v117, v108, v93
	s_waitcnt lgkmcnt(9)
	v_mul_f32_e32 v118, v109, v94
	s_waitcnt lgkmcnt(8)
	v_mul_f32_e32 v119, v110, v95
	s_waitcnt lgkmcnt(7)
	v_mul_f32_e32 v120, v104, v96
	s_waitcnt lgkmcnt(6)
	v_mul_f32_e32 v121, v105, v97
	s_waitcnt lgkmcnt(5)
	v_mul_f32_e32 v122, v106, v98
	s_waitcnt lgkmcnt(4)
	v_mul_f32_e32 v123, v107, v99
	s_waitcnt lgkmcnt(3)
	v_mul_f32_e32 v124, v108, v100
	s_waitcnt lgkmcnt(2)
	v_mul_f32_e32 v125, v109, v101
	s_waitcnt lgkmcnt(1)
	v_mul_f32_e32 v126, v110, v102
	s_waitcnt lgkmcnt(0)
	v_mul_f32_e32 v127, v111, v103
	ds_write_b32 v76, v112
	ds_write_b32 v77, v113
	ds_write_b32 v78, v114
	ds_write_b32 v79, v115
	ds_write_b32 v76, v116 offset:64
	ds_write_b32 v77, v117 offset:64
	ds_write_b32 v78, v118 offset:64
	ds_write_b32 v79, v119 offset:64
	ds_write_b32 v76, v120 offset:128
	ds_write_b32 v77, v121 offset:128
	ds_write_b32 v78, v122 offset:128
	ds_write_b32 v79, v123 offset:128
	ds_write_b32 v76, v124 offset:192
	ds_write_b32 v77, v125 offset:192
	ds_write_b32 v78, v126 offset:192
	ds_write_b32 v79, v127 offset:192
.Lmy_ck_drB_h:
	s_waitcnt lgkmcnt(0)
	s_nop 0
	ds_read_b32 v88, v72 offset:16384
	ds_read_b32 v89, v72 offset:16640
	ds_read_b32 v90, v72 offset:16896
	ds_read_b32 v91, v72 offset:17152
	ds_read_b32 v92, v72 offset:17408
	ds_read_b32 v93, v72 offset:17664
	ds_read_b32 v94, v72 offset:17920
	ds_read_b32 v95, v72 offset:18176
	ds_read_b32 v96, v72 offset:24576
	ds_read_b32 v97, v72 offset:24832
	ds_read_b32 v98, v72 offset:25088
	ds_read_b32 v99, v72 offset:25344
	ds_read_b32 v100, v72 offset:25600
	ds_read_b32 v101, v72 offset:25856
	ds_read_b32 v102, v72 offset:26112
	ds_read_b32 v103, v72 offset:26368
	v_and_b32_e32 v74, 15, v224
	v_lshrrev_b32_e32 v76, 4, v224
	v_lshlrev_b32_e64 v74, 4, v74
	v_lshl_add_u32 v74, v76, 10, v74
	s_add_i32 s101, s97, 0x1000
	v_add_u32_e64 v74, s101, v74
	s_add_i32 s101, s97, 0x2000
	v_lshl_add_u32 v75, v224, 2, s101
	v_mov_b32_e32 v104, v80
	v_mul_f32_e32 v105, v104, v81
	v_mul_f32_e32 v106, v105, v82
	v_mul_f32_e32 v107, v106, v83
	v_mul_f32_e32 v108, v107, v84
	v_mul_f32_e32 v109, v108, v85
	v_mul_f32_e32 v110, v109, v86
	v_mul_f32_e32 v111, v110, v87
	v_rcp_f32_e32 v112, v104
	v_rcp_f32_e32 v113, v105
	v_rcp_f32_e32 v114, v106
	v_rcp_f32_e32 v115, v107
	v_rcp_f32_e32 v116, v108
	v_rcp_f32_e32 v117, v109
	v_rcp_f32_e32 v118, v110
	v_rcp_f32_e32 v119, v111
	s_waitcnt lgkmcnt(7)
	v_mul_f32_e32 v120, v112, v96
	s_waitcnt lgkmcnt(6)
	v_mul_f32_e32 v121, v113, v97
	s_waitcnt lgkmcnt(5)
	v_mul_f32_e32 v122, v114, v98
	s_waitcnt lgkmcnt(4)
	v_mul_f32_e32 v123, v115, v99
	s_waitcnt lgkmcnt(3)
	v_mul_f32_e32 v124, v116, v100
	s_waitcnt lgkmcnt(2)
	v_mul_f32_e32 v125, v117, v101
	s_waitcnt lgkmcnt(1)
	v_mul_f32_e32 v126, v118, v102
	s_waitcnt lgkmcnt(0)
	v_mul_f32_e32 v127, v119, v103
	v_mul_f32_e32 v112, v112, v88
	v_mul_f32_e32 v113, v113, v89
	v_mul_f32_e32 v114, v114, v90
	v_mul_f32_e32 v115, v115, v91
	v_mul_f32_e32 v116, v116, v92
	v_mul_f32_e32 v117, v117, v93
	v_mul_f32_e32 v118, v118, v94
	v_mul_f32_e32 v119, v119, v95
	ds_write_b128 v74, v[112:115]
	ds_write_b128 v74, v[116:119] offset:256
	ds_write_b128 v74, v[120:123] offset:512
	ds_write_b128 v74, v[124:127] offset:768
	ds_write_b32 v75, v111
.Lmy_ck_drE_h:
	s_waitcnt lgkmcnt(0)
	s_nop 0
	s_bfe_u32 s96, s62, 0x20006
	s_and_b32 s97, s96, 1
	s_nop 0
	s_mul_i32 s97, s97, 0x2700
	s_mov_b32 s101, 0x1c000
	s_mov_b32 s100, 0x6100
	s_bitcmp0_b32 s65, 0
	s_nop 0
	s_cselect_b32 s101, 0xe000, s101
	s_cselect_b32 s100, 0x4e00, s100
	s_cmp_gt_u32 s96, 1
	s_cselect_b32 s100, s100, 0
	s_add_i32 s97, s97, s101
	s_add_i32 s97, s97, s100
	s_mov_b32 s96, s97
	v_and_b32_e32 v72, 3, v233
	v_lshrrev_b32_e32 v73, 2, v233
	v_lshlrev_b32_e32 v72, 2, v72
	v_lshl_add_u32 v72, v73, 8, v72
	v_lshl_add_u32 v72, v234, 6, v72
	s_add_i32 s97, s96, 0x1000
	v_add_u32_e32 v78, s97, v72
	v_xor_b32_e32 v79, v224, v234
	v_lshl_add_u32 v79, v79, 4, s96
	ds_read_b128 v[96:99], v79
	ds_read_b128 v[100:103], v79 offset:1024
	ds_read_b128 v[104:107], v79 offset:2048
	ds_read_b128 v[108:111], v79 offset:3072
	ds_read_b32 v80, v78
	ds_read_b32 v81, v78 offset:16
	ds_read_b32 v82, v78 offset:32
	ds_read_b32 v83, v78 offset:48
	ds_read_b32 v84, v78 offset:1024
	ds_read_b32 v85, v78 offset:1040
	ds_read_b32 v86, v78 offset:1056
	ds_read_b32 v87, v78 offset:1072
	ds_read_b32 v88, v78 offset:2048
	ds_read_b32 v89, v78 offset:2064
	ds_read_b32 v90, v78 offset:2080
	ds_read_b32 v91, v78 offset:2096
	ds_read_b32 v92, v78 offset:3072
	ds_read_b32 v93, v78 offset:3088
	ds_read_b32 v94, v78 offset:3104
	ds_read_b32 v95, v78 offset:3120
	v_lshl_add_u32 v74, v224, 2, s96
	ds_write_b32 v74, v235 offset:9728
	v_add_u32_e32 v75, -1, v233
	v_mov_b32_e32 v76, -1
	v_cndmask_b32_e64 v75, v76, v75, s[98:99]
	v_cmp_lt_u32_e64 s[100:101], 7, v233
	v_add_u32_e32 v76, -8, v233
	v_and_b32_e32 v77, 1, v234
	v_cndmask_b32_e64 v75, v75, v76, s[100:101]
	v_lshlrev_b32_e32 v77, 2, v77
	v_sub_u32_e32 v76, v75, v77
	v_lshlrev_b32_e32 v77, 2, v234
	v_sub_u32_e32 v77, v233, v77
	v_add_u32_e32 v77, -1, v77
	s_waitcnt lgkmcnt(15)
	v_mfma_f32_16x16x4_f32 v[244:247], v80, v96, 0
	v_mfma_f32_16x16x4_f32 v[240:243], v81, v97, 0
	s_waitcnt lgkmcnt(14)
	s_nop 0
	v_mfma_f32_16x16x4_f32 v[244:247], v82, v98, v[244:247]
	s_waitcnt lgkmcnt(13)
	s_nop 0
	v_mfma_f32_16x16x4_f32 v[240:243], v83, v99, v[240:243]
	s_waitcnt lgkmcnt(12)
	s_nop 0
	v_mfma_f32_16x16x4_f32 v[244:247], v84, v100, v[244:247]
	s_waitcnt lgkmcnt(11)
	s_nop 0
	v_mfma_f32_16x16x4_f32 v[240:243], v85, v101, v[240:243]
	s_waitcnt lgkmcnt(10)
	s_nop 0
	v_mfma_f32_16x16x4_f32 v[244:247], v86, v102, v[244:247]
	s_waitcnt lgkmcnt(9)
	s_nop 0
	v_mfma_f32_16x16x4_f32 v[240:243], v87, v103, v[240:243]
	s_waitcnt lgkmcnt(8)
	s_nop 0
	v_mfma_f32_16x16x4_f32 v[244:247], v88, v104, v[244:247]
	s_waitcnt lgkmcnt(7)
	s_nop 0
	v_mfma_f32_16x16x4_f32 v[240:243], v89, v105, v[240:243]
	s_waitcnt lgkmcnt(6)
	s_nop 0
	v_mfma_f32_16x16x4_f32 v[244:247], v90, v106, v[244:247]
	s_waitcnt lgkmcnt(5)
	s_nop 0
	v_mfma_f32_16x16x4_f32 v[240:243], v91, v107, v[240:243]
	s_waitcnt lgkmcnt(4)
	s_nop 0
	v_mfma_f32_16x16x4_f32 v[244:247], v92, v108, v[244:247]
	s_waitcnt lgkmcnt(3)
	s_nop 0
	v_mfma_f32_16x16x4_f32 v[240:243], v93, v109, v[240:243]
	s_waitcnt lgkmcnt(2)
	s_nop 0
	v_mfma_f32_16x16x4_f32 v[244:247], v94, v110, v[244:247]
	s_waitcnt lgkmcnt(1)
	s_nop 0
	v_mfma_f32_16x16x4_f32 v[240:243], v95, v111, v[240:243]
	s_nop 9
	v_add_f32_e32 v244, v244, v240
	v_add_f32_e32 v245, v245, v241
	v_add_f32_e32 v246, v246, v242
	v_add_f32_e64 v247, v247, v243
	v_cmp_le_i32_e64 s[96:97], 0, v76
	v_cmp_le_i32_e64 s[100:101], 1, v76
	s_nop 0
	s_nop 0
	v_cndmask_b32_e64 v128, 0, v244, s[96:97]
	v_cndmask_b32_e64 v129, 0, v245, s[100:101]
	v_cmp_le_i32_e64 s[96:97], 2, v76
	v_cmp_le_i32_e64 s[100:101], 3, v76
	s_nop 0
	s_nop 0
	v_cndmask_b32_e64 v130, 0, v246, s[96:97]
	v_cndmask_b32_e64 v131, 0, v247, s[100:101]
	s_bfe_u32 s96, s62, 0x20006
	s_and_b32 s97, s96, 1
	s_nop 0
	s_mul_i32 s97, s97, 0x2700
	s_mov_b32 s101, 0x1c000
	s_mov_b32 s100, 0x6100
	s_bitcmp0_b32 s65, 0
	s_nop 0
	s_cselect_b32 s101, 0xe000, s101
	s_cselect_b32 s100, 0x4e00, s100
	s_cmp_gt_u32 s96, 1
	s_cselect_b32 s100, s100, 0
	s_add_i32 s97, s97, s101
	s_add_i32 s97, s97, s100
	v_xor_b32_e64 v74, v224, v234
	v_lshl_add_u32 v74, v74, 4, s97
	ds_write_b128 v74, v[128:131] offset:8448
	v_lshlrev_b32_e64 v75, 7, v234
	v_lshl_add_u32 v75, v233, 2, v75
	v_add_u32_e64 v75, s97, v75
	v_cmp_le_i32_e64 s[96:97], 0, v77
	v_cmp_le_i32_e64 s[100:101], 1, v77
	s_nop 0
	s_nop 0
	v_cndmask_b32_e64 v132, 0, v244, s[96:97]
	v_cndmask_b32_e64 v133, 0, v245, s[100:101]
	v_cmp_le_i32_e64 s[96:97], 2, v77
	v_cmp_le_i32_e64 s[100:101], 3, v77
	s_nop 0
	s_nop 0
	v_cndmask_b32_e64 v134, 0, v246, s[96:97]
	v_cndmask_b32_e64 v135, 0, v247, s[100:101]
	s_mov_b64 exec, 0x00ff00ff
	ds_write_b32 v75, v132 offset:9472
	ds_write_b32 v75, v133 offset:9504
	ds_write_b32 v75, v134 offset:9536
	ds_write_b32 v75, v135 offset:9568
	s_mov_b64 exec, -1
	s_setprio 0
	s_branch .LBB0_655
	s_nop 0
	s_nop 0
	s_nop 0
	s_nop 0
	s_nop 0
	s_nop 0
	s_nop 0
	s_nop 0
	s_nop 0
	s_nop 0
	s_nop 0
	s_nop 0
	s_nop 0
	s_nop 0
	s_nop 0
	s_nop 0
	s_nop 0
	s_nop 0
	s_nop 0
	s_nop 0
	s_nop 0
	s_nop 0
	s_nop 0
	s_nop 0
	s_nop 0
	s_nop 0
	s_nop 0
	s_nop 0
	s_nop 0
	s_nop 0
	s_nop 0
	s_nop 0
	s_nop 0
	s_nop 0
	s_nop 0
	s_nop 0
	s_nop 0
	s_nop 0
	s_nop 0
	s_nop 0
	s_nop 0
	s_nop 0
	s_nop 0
	s_nop 0
	s_nop 0
	s_nop 0
	s_nop 0
	s_nop 0
	s_nop 0
	s_nop 0
	s_nop 0
	s_nop 0
	s_nop 0
	s_nop 0
	s_nop 0
	s_nop 0
	s_nop 0
	s_nop 0
	s_nop 0
	s_nop 0
	s_nop 0
	s_nop 0
	s_nop 0
	s_nop 0
	s_nop 0
	s_nop 0
	s_nop 0
	s_nop 0
	s_nop 0
	s_nop 0
